# mirror experiment: s_setprio 1 during the recurrence part of the S5 scan blocks instead of during the MFMA issue
# baseline (speedup 1.0000x reference)
; #define HB (__builtin_amdgcn_readfirstlane(otid_full() >> 8))
; __device__ __forceinline__ void phaseB(const Params& p, int layer, char* sm0) {
;   const int total = 512 + 2048 + 2048;
;   char* sm = sm0 + HB * HALF_LDS;
;   for (int t = VB; t < total; t += G2) {
;     if (t < 512) ssd_pass1(p, layer, t, sm);
;     else if (t < 2560) s5_pass1(p, layer, t - 512, sm);
;     else mem_attn(p, layer, t - 2560);
;   }
; }
; __device__ __forceinline__ void phaseC(const Params& p, int layer, char* sm0, bool dsa_only) {
;   const int G = G2;
;   const int total = dsa_only ? 1024 : 1024 + 256 + 16;
;   char* sm = sm0 + HB * HALF_LDS;
;   int rr = 0;
;   for (int i = VB; i < total; i += G, rr++) {
;     if (i < 1024) {
;       int pos = i - rr * G; int idx = i;
;       if ((rr & 1) && (rr * G + G <= 1024)) idx = rr * G + (G - 1 - pos);
.LBB0_190:
	s_or_b64 exec, exec, s[0:1]
	v_readlane_b32 s20, v253, 2
	s_lshl_b32 s22, s20, 1
	s_add_i32 s0, s22, 0xfffffff
	s_cmpk_lg_i32 s20, 0x100
	v_writelane_b32 v253, s0, 48
	s_cselect_b64 s[0:1], -1, 0
	v_writelane_b32 v253, s0, 49
	v_mbcnt_lo_u32_b32 v0, -1, 0
	s_mov_b32 s69, 0
	v_writelane_b32 v253, s1, 50
	v_mov_b32_e32 v145, 0
	s_setprio 0
	v_readlane_b32 s2, v253, 20
	v_readlane_b32 s3, v253, 21
	v_readlane_b32 s4, v253, 22
	s_lshl_b64 s[0:1], s[2:3], 17
	v_readlane_b32 s14, v253, 32
	v_readlane_b32 s15, v253, 33
	s_add_u32 s0, s14, s0
	s_addc_u32 s1, s15, s1
	v_readlane_b32 s5, v253, 23
	v_readlane_b32 s6, v253, 24
	v_readlane_b32 s7, v253, 25
	v_readlane_b32 s8, v253, 26
	v_readlane_b32 s9, v253, 27
	v_readlane_b32 s10, v253, 28
	v_readlane_b32 s11, v253, 29
	v_readlane_b32 s12, v253, 30
	v_readlane_b32 s13, v253, 31
	v_readlane_b32 s16, v253, 34
	v_readlane_b32 s17, v253, 35
	v_readlane_b32 s18, v253, 36
	v_readlane_b32 s19, v253, 37
	v_writelane_b32 v253, s0, 51
	s_cmpk_lt_i32 s2, 0x400
	v_readlane_b32 s4, v252, 32
	v_writelane_b32 v253, s1, 52
	s_cselect_b64 s[0:1], -1, 0
	v_writelane_b32 v253, s0, 53
	v_readlane_b32 s5, v252, 33
	v_readlane_b32 s12, v252, 40
	v_writelane_b32 v253, s1, 54
	s_lshl_b32 s0, s2, 19
	v_writelane_b32 v253, s0, 55
	s_lshl_b32 s0, s20, 19
	v_writelane_b32 v253, s0, 56
	s_add_i32 s0, s2, 0xfffff480
	v_writelane_b32 v253, s0, 57
	s_lshl_b32 s0, s2, 8
	v_writelane_b32 v253, s0, 58
	s_lshl_b32 s0, s20, 8
	v_writelane_b32 v253, s0, 59
	s_add_u32 s0, s4, 4
	s_addc_u32 s1, s5, 0
	v_writelane_b32 v253, s0, 60
	v_readlane_b32 s6, v252, 34
	v_readlane_b32 s7, v252, 35
	v_writelane_b32 v253, s1, 61
	v_readlane_b32 s8, v252, 36
	v_readlane_b32 s21, v253, 19
	s_add_i32 s0, s21, 0xffffff00
	v_writelane_b32 v253, s0, 62
	s_lshl_b32 s0, s20, 7
	v_readlane_b32 s9, v252, 37
	v_readlane_b32 s10, v252, 38
	v_readlane_b32 s11, v252, 39
	v_readlane_b32 s13, v252, 41
	v_readlane_b32 s14, v252, 42
	v_readlane_b32 s15, v252, 43
	v_readlane_b32 s16, v252, 44
	v_readlane_b32 s17, v252, 45
	v_readlane_b32 s18, v252, 46
	v_readlane_b32 s19, v252, 47
	v_writelane_b32 v253, s0, 63
	s_add_u32 s0, s12, 0x78
	v_writelane_b32 v254, s0, 0
	s_addc_u32 s0, s13, 0
	v_readlane_b32 s4, v252, 16
	v_readlane_b32 s12, v252, 24
	v_readlane_b32 s13, v252, 25
	v_readlane_b32 s14, v252, 26
	v_readlane_b32 s15, v252, 27
	v_readlane_b32 s16, v252, 28
	v_readlane_b32 s17, v252, 29
	v_readlane_b32 s18, v252, 30
	v_readlane_b32 s19, v252, 31
	s_mov_b64 s[12:13], s[16:17]
	v_writelane_b32 v254, s0, 1
	s_add_u32 s0, s12, 0x80
	v_writelane_b32 v254, s0, 2
	s_addc_u32 s0, s13, 0
	v_writelane_b32 v254, s0, 3
	s_mul_i32 s0, s2, 6
	v_readlane_b32 s5, v252, 17
	v_readlane_b32 s6, v252, 18
	v_readlane_b32 s7, v252, 19
	v_readlane_b32 s8, v252, 20
	v_readlane_b32 s9, v252, 21
	v_readlane_b32 s10, v252, 22
	v_readlane_b32 s11, v252, 23
	s_mov_b64 s[14:15], s[18:19]
	s_addk_i32 s0, 0xfe00
	v_writelane_b32 v254, s0, 4
	v_readlane_b32 s0, v252, 48
	v_readlane_b32 s10, v252, 58
	v_readlane_b32 s1, v252, 49
	v_readlane_b32 s11, v252, 59
	s_add_u32 s0, s10, 0x3c08
	s_addc_u32 s1, s11, 0
	v_writelane_b32 v254, s0, 5
	s_ashr_i32 s23, s22, 31
	v_readlane_b32 s2, v252, 50
	v_writelane_b32 v254, s1, 6
	s_ashr_i32 s0, s21, 31
	v_writelane_b32 v254, s0, 7
	s_lshl_b64 s[0:1], s[22:23], 16
	v_readlane_b32 s3, v252, 51
	v_readlane_b32 s4, v252, 52
	v_readlane_b32 s5, v252, 53
	v_readlane_b32 s6, v252, 54
	v_readlane_b32 s7, v252, 55
	v_readlane_b32 s8, v252, 56
	v_readlane_b32 s9, v252, 57
	v_readlane_b32 s12, v252, 60
	v_readlane_b32 s13, v252, 61
	v_readlane_b32 s14, v252, 62
	v_readlane_b32 s15, v252, 63
	v_writelane_b32 v254, s0, 8
	v_mov_b32_e32 v206, 1
	v_mbcnt_hi_u32_b32 v202, -1, v0
	v_writelane_b32 v254, s1, 9
	v_readlane_b32 s0, v253, 3
	v_readlane_b32 s8, v253, 11
	v_readlane_b32 s1, v253, 4
	v_readlane_b32 s9, v253, 12
	s_add_u32 s0, s8, 0x1000
	s_addc_u32 s1, s9, 0
	v_writelane_b32 v254, s0, 10
	v_readlane_b32 s10, v253, 13
	v_readlane_b32 s11, v253, 14
	v_writelane_b32 v254, s1, 11
	s_mov_b32 s0, s22
	v_writelane_b32 v254, s0, 12
	s_lshl_b64 s[10:11], s[22:23], 15
	v_bfrev_b32_e32 v207, 1
	v_writelane_b32 v254, s1, 13
	s_mov_b64 s[0:1], -1
	v_writelane_b32 v254, s0, 14
	v_mov_b32_e32 v208, 0xff800000
	v_mov_b32_e32 v209, 0xff61b1e6
	v_writelane_b32 v254, s1, 15
	v_writelane_b32 v254, s10, 16
	s_movk_i32 s24, 0xb88
	s_movk_i32 s96, 0x2d00
	s_movk_i32 s47, 0x1654
	s_movk_i32 s48, 0xa43
	s_movk_i32 s97, 0x1200
	s_movk_i32 s33, 0x3fff
	s_movk_i32 s80, 0x1e0
	s_brev_b32 s81, 1
	s_movk_i32 s82, 0xc000
	s_mov_b32 s83, 0xfe967699
	s_mov_b64 s[50:51], 0x80
	s_mov_b64 s[74:75], 0x80080
	s_mov_b64 s[70:71], 0x100
	s_mov_b64 s[76:77], 0x80100
	s_mov_b64 s[78:79], 0x60
	s_mov_b64 s[84:85], 0x80180
	s_mov_b64 s[72:73], 0x180
	s_mov_b32 s86, s69
	v_writelane_b32 v254, s11, 17
	s_barrier
	v_readlane_b32 s2, v253, 5
	v_readlane_b32 s3, v253, 6
	v_readlane_b32 s4, v253, 7
	v_readlane_b32 s5, v253, 8
	v_readlane_b32 s6, v253, 9
	v_readlane_b32 s7, v253, 10
	v_readlane_b32 s12, v253, 15
	v_readlane_b32 s13, v253, 16
	v_readlane_b32 s14, v253, 17
	v_readlane_b32 s15, v253, 18
	s_branch .LBB0_194

; __device__ __forceinline__ void s5_pass1(const Params& p, int layer, int task, char* sm) {
;     ...
;   for (int l = 0; l < 128; l++) S5_STEP(sU + l * 16)
.LBB0_477:
	v_mov_b32_e32 v37, v38
	s_nop 1
	v_permlane32_swap_b32_e32 v16, v12
	v_permlane32_swap_b32_e32 v17, v13
	v_permlane32_swap_b32_e32 v18, v14
	v_permlane32_swap_b32_e32 v19, v15
	v_permlane32_swap_b32_e32 v20, v8
	v_permlane32_swap_b32_e32 v21, v9
	v_permlane32_swap_b32_e32 v22, v10
	v_permlane32_swap_b32_e32 v23, v11
	v_permlane32_swap_b32_e32 v24, v4
	v_permlane32_swap_b32_e32 v25, v5
	v_permlane32_swap_b32_e32 v26, v6
	v_permlane32_swap_b32_e32 v27, v7
	v_permlane32_swap_b32_e32 v28, v0
	v_permlane32_swap_b32_e32 v29, v1
	v_permlane32_swap_b32_e32 v30, v2
	v_permlane32_swap_b32_e32 v31, v3
	v_and_b32_e32 v186, 31, v202
	v_lshrrev_b32_e32 v187, 5, v202
	v_lshlrev_b32_e32 v186, 6, v186
	v_lshl_add_u32 v186, v187, 2, v186
	v_add_u32_e32 v186, v41, v186
	ds_read2_b32 v[178:179], v186 offset0:0 offset1:2
	ds_read2_b32 v[180:181], v186 offset0:4 offset1:6
	ds_read2_b32 v[182:183], v186 offset0:8 offset1:10
	ds_read2_b32 v[184:185], v186 offset0:12 offset1:14
	s_waitcnt lgkmcnt(0)
	v_add_u32_e32 v186, 0x800, v186
	s_setprio 0
	v_mfma_f32_32x32x2_f32 v[108:123], v178, v16, 0
	v_mfma_f32_32x32x2_f32 v[124:139], v178, v17, 0
	v_mfma_f32_32x32x2_f32 v[146:161], v178, v12, 0
	v_mfma_f32_32x32x2_f32 v[162:177], v178, v13, 0
	v_mfma_f32_32x32x2_f32 v[108:123], v179, v18, v[108:123]
	v_mfma_f32_32x32x2_f32 v[124:139], v179, v19, v[124:139]
	v_mfma_f32_32x32x2_f32 v[146:161], v179, v14, v[146:161]
	v_mfma_f32_32x32x2_f32 v[162:177], v179, v15, v[162:177]
	v_mfma_f32_32x32x2_f32 v[108:123], v180, v20, v[108:123]
	v_mfma_f32_32x32x2_f32 v[124:139], v180, v21, v[124:139]
	v_mfma_f32_32x32x2_f32 v[146:161], v180, v8, v[146:161]
	v_mfma_f32_32x32x2_f32 v[162:177], v180, v9, v[162:177]
	v_mfma_f32_32x32x2_f32 v[108:123], v181, v22, v[108:123]
	v_mfma_f32_32x32x2_f32 v[124:139], v181, v23, v[124:139]
	v_mfma_f32_32x32x2_f32 v[146:161], v181, v10, v[146:161]
	v_mfma_f32_32x32x2_f32 v[162:177], v181, v11, v[162:177]
	v_mfma_f32_32x32x2_f32 v[108:123], v182, v24, v[108:123]
	v_mfma_f32_32x32x2_f32 v[124:139], v182, v25, v[124:139]
	v_mfma_f32_32x32x2_f32 v[146:161], v182, v4, v[146:161]
	v_mfma_f32_32x32x2_f32 v[162:177], v182, v5, v[162:177]
	v_mfma_f32_32x32x2_f32 v[108:123], v183, v26, v[108:123]
	v_mfma_f32_32x32x2_f32 v[124:139], v183, v27, v[124:139]
	v_mfma_f32_32x32x2_f32 v[146:161], v183, v6, v[146:161]
	v_mfma_f32_32x32x2_f32 v[162:177], v183, v7, v[162:177]
	v_mfma_f32_32x32x2_f32 v[108:123], v184, v28, v[108:123]
	v_mfma_f32_32x32x2_f32 v[124:139], v184, v29, v[124:139]
	v_mfma_f32_32x32x2_f32 v[146:161], v184, v0, v[146:161]
	v_mfma_f32_32x32x2_f32 v[162:177], v184, v1, v[162:177]
	v_mfma_f32_32x32x2_f32 v[108:123], v185, v30, v[108:123]
	v_mfma_f32_32x32x2_f32 v[124:139], v185, v31, v[124:139]
	v_mfma_f32_32x32x2_f32 v[146:161], v185, v2, v[146:161]
	v_mfma_f32_32x32x2_f32 v[162:177], v185, v3, v[162:177]
	s_setprio 1
	s_nop 7
	s_nop 7
	s_nop 7
	v_permlane32_swap_b32_e32 v108, v146
	v_permlane32_swap_b32_e32 v124, v162
	v_permlane32_swap_b32_e32 v109, v147
	v_permlane32_swap_b32_e32 v125, v163
	v_permlane32_swap_b32_e32 v110, v148
	v_permlane32_swap_b32_e32 v126, v164
	v_permlane32_swap_b32_e32 v111, v149
	v_permlane32_swap_b32_e32 v127, v165
	v_permlane32_swap_b32_e32 v112, v150
	v_permlane32_swap_b32_e32 v128, v166
	v_permlane32_swap_b32_e32 v113, v151
	v_permlane32_swap_b32_e32 v129, v167
	v_permlane32_swap_b32_e32 v114, v152
	v_permlane32_swap_b32_e32 v130, v168
	v_permlane32_swap_b32_e32 v115, v153
	v_permlane32_swap_b32_e32 v131, v169
	v_permlane32_swap_b32_e32 v116, v154
	v_permlane32_swap_b32_e32 v132, v170
	v_permlane32_swap_b32_e32 v117, v155
	v_permlane32_swap_b32_e32 v133, v171
	v_permlane32_swap_b32_e32 v118, v156
	v_permlane32_swap_b32_e32 v134, v172
	v_permlane32_swap_b32_e32 v119, v157
	v_permlane32_swap_b32_e32 v135, v173
	v_permlane32_swap_b32_e32 v120, v158
	v_permlane32_swap_b32_e32 v136, v174
	v_permlane32_swap_b32_e32 v121, v159
	v_permlane32_swap_b32_e32 v137, v175
	v_permlane32_swap_b32_e32 v122, v160
	v_permlane32_swap_b32_e32 v138, v176
	v_permlane32_swap_b32_e32 v123, v161
	v_permlane32_swap_b32_e32 v139, v177
	v_mul_f32_e32 v188, v34, v37
	v_mul_f32_e32 v189, v35, v37
	v_fma_f32 v190, v32, v36, -v188
	v_fma_f32 v191, v33, v36, v189
	v_add_f32_e32 v36, v190, v108
	v_add_f32_e32 v37, v191, v124
	v_mul_f32_e32 v188, v34, v37
	v_mul_f32_e32 v189, v35, v37
	v_fma_f32 v190, v32, v36, -v188
	v_fma_f32 v191, v33, v36, v189
	v_add_f32_e32 v36, v190, v109
	v_add_f32_e32 v37, v191, v125
	v_mul_f32_e32 v188, v34, v37
	v_mul_f32_e32 v189, v35, v37
	v_fma_f32 v190, v32, v36, -v188
	v_fma_f32 v191, v33, v36, v189
	v_add_f32_e32 v36, v190, v110
	v_add_f32_e32 v37, v191, v126
	v_mul_f32_e32 v188, v34, v37
	v_mul_f32_e32 v189, v35, v37
	v_fma_f32 v190, v32, v36, -v188
	v_fma_f32 v191, v33, v36, v189
	v_add_f32_e32 v36, v190, v111
	v_add_f32_e32 v37, v191, v127
	v_mul_f32_e32 v188, v34, v37
	v_mul_f32_e32 v189, v35, v37
	v_fma_f32 v190, v32, v36, -v188
	v_fma_f32 v191, v33, v36, v189
	v_add_f32_e32 v36, v190, v146
	v_add_f32_e32 v37, v191, v162
	v_mul_f32_e32 v188, v34, v37
	v_mul_f32_e32 v189, v35, v37
	v_fma_f32 v190, v32, v36, -v188
	v_fma_f32 v191, v33, v36, v189
	v_add_f32_e32 v36, v190, v147
	v_add_f32_e32 v37, v191, v163
	v_mul_f32_e32 v188, v34, v37
	v_mul_f32_e32 v189, v35, v37
	v_fma_f32 v190, v32, v36, -v188
	v_fma_f32 v191, v33, v36, v189
	v_add_f32_e32 v36, v190, v148
	v_add_f32_e32 v37, v191, v164
	v_mul_f32_e32 v188, v34, v37
	v_mul_f32_e32 v189, v35, v37
	v_fma_f32 v190, v32, v36, -v188
	v_fma_f32 v191, v33, v36, v189
	v_add_f32_e32 v36, v190, v149
	v_add_f32_e32 v37, v191, v165
	v_mul_f32_e32 v188, v34, v37
; __device__ __forceinline__ void s5_pass1(const Params& p, int layer, int task, char* sm) {
;     ...
;   for (int l = 0; l < 128; l++) S5_STEP(sU + l * 16)
	v_mul_f32_e32 v189, v35, v37
	v_fma_f32 v190, v32, v36, -v188
	v_fma_f32 v191, v33, v36, v189
	v_add_f32_e32 v36, v190, v112
	v_add_f32_e32 v37, v191, v128
	v_mul_f32_e32 v188, v34, v37
	v_mul_f32_e32 v189, v35, v37
	v_fma_f32 v190, v32, v36, -v188
	v_fma_f32 v191, v33, v36, v189
	v_add_f32_e32 v36, v190, v113
	v_add_f32_e32 v37, v191, v129
	v_mul_f32_e32 v188, v34, v37
	v_mul_f32_e32 v189, v35, v37
	v_fma_f32 v190, v32, v36, -v188
	v_fma_f32 v191, v33, v36, v189
	v_add_f32_e32 v36, v190, v114
	v_add_f32_e32 v37, v191, v130
	v_mul_f32_e32 v188, v34, v37
	v_mul_f32_e32 v189, v35, v37
	v_fma_f32 v190, v32, v36, -v188
	v_fma_f32 v191, v33, v36, v189
	v_add_f32_e32 v36, v190, v115
	v_add_f32_e32 v37, v191, v131
	v_mul_f32_e32 v188, v34, v37
	v_mul_f32_e32 v189, v35, v37
	v_fma_f32 v190, v32, v36, -v188
	v_fma_f32 v191, v33, v36, v189
	v_add_f32_e32 v36, v190, v150
	v_add_f32_e32 v37, v191, v166
	v_mul_f32_e32 v188, v34, v37
	v_mul_f32_e32 v189, v35, v37
	v_fma_f32 v190, v32, v36, -v188
	v_fma_f32 v191, v33, v36, v189
	v_add_f32_e32 v36, v190, v151
	v_add_f32_e32 v37, v191, v167
	v_mul_f32_e32 v188, v34, v37
	v_mul_f32_e32 v189, v35, v37
	v_fma_f32 v190, v32, v36, -v188
	v_fma_f32 v191, v33, v36, v189
	v_add_f32_e32 v36, v190, v152
	v_add_f32_e32 v37, v191, v168
	v_mul_f32_e32 v188, v34, v37
	v_mul_f32_e32 v189, v35, v37
	v_fma_f32 v190, v32, v36, -v188
	v_fma_f32 v191, v33, v36, v189
	v_add_f32_e32 v36, v190, v153
	v_add_f32_e32 v37, v191, v169
	v_mul_f32_e32 v188, v34, v37
	v_mul_f32_e32 v189, v35, v37
	v_fma_f32 v190, v32, v36, -v188
	v_fma_f32 v191, v33, v36, v189
	v_add_f32_e32 v36, v190, v116
	v_add_f32_e32 v37, v191, v132
	v_mul_f32_e32 v188, v34, v37
	v_mul_f32_e32 v189, v35, v37
	v_fma_f32 v190, v32, v36, -v188
	v_fma_f32 v191, v33, v36, v189
	v_add_f32_e32 v36, v190, v117
	v_add_f32_e32 v37, v191, v133
	v_mul_f32_e32 v188, v34, v37
	v_mul_f32_e32 v189, v35, v37
	v_fma_f32 v190, v32, v36, -v188
	v_fma_f32 v191, v33, v36, v189
	v_add_f32_e32 v36, v190, v118
	v_add_f32_e32 v37, v191, v134
	v_mul_f32_e32 v188, v34, v37
	v_mul_f32_e32 v189, v35, v37
	v_fma_f32 v190, v32, v36, -v188
	v_fma_f32 v191, v33, v36, v189
	v_add_f32_e32 v36, v190, v119
	v_add_f32_e32 v37, v191, v135
	v_mul_f32_e32 v188, v34, v37
	v_mul_f32_e32 v189, v35, v37
	v_fma_f32 v190, v32, v36, -v188
	v_fma_f32 v191, v33, v36, v189
	v_add_f32_e32 v36, v190, v154
	v_add_f32_e32 v37, v191, v170
	v_mul_f32_e32 v188, v34, v37
	v_mul_f32_e32 v189, v35, v37
	v_fma_f32 v190, v32, v36, -v188
	v_fma_f32 v191, v33, v36, v189
	v_add_f32_e32 v36, v190, v155
	v_add_f32_e32 v37, v191, v171
	v_mul_f32_e32 v188, v34, v37
	v_mul_f32_e32 v189, v35, v37
	v_fma_f32 v190, v32, v36, -v188
	v_fma_f32 v191, v33, v36, v189
	v_add_f32_e32 v36, v190, v156
	v_add_f32_e32 v37, v191, v172
	v_mul_f32_e32 v188, v34, v37
	v_mul_f32_e32 v189, v35, v37
	v_fma_f32 v190, v32, v36, -v188
	v_fma_f32 v191, v33, v36, v189
	v_add_f32_e32 v36, v190, v157
	v_add_f32_e32 v37, v191, v173
	v_mul_f32_e32 v188, v34, v37
	v_mul_f32_e32 v189, v35, v37
	v_fma_f32 v190, v32, v36, -v188
	v_fma_f32 v191, v33, v36, v189
	v_add_f32_e32 v36, v190, v120
	v_add_f32_e32 v37, v191, v136
	v_mul_f32_e32 v188, v34, v37
	v_mul_f32_e32 v189, v35, v37
	v_fma_f32 v190, v32, v36, -v188
	v_fma_f32 v191, v33, v36, v189
	v_add_f32_e32 v36, v190, v121
	v_add_f32_e32 v37, v191, v137
	v_mul_f32_e32 v188, v34, v37
	v_mul_f32_e32 v189, v35, v37
	v_fma_f32 v190, v32, v36, -v188
	v_fma_f32 v191, v33, v36, v189
	v_add_f32_e32 v36, v190, v122
	v_add_f32_e32 v37, v191, v138
	v_mul_f32_e32 v188, v34, v37
	v_mul_f32_e32 v189, v35, v37
	v_fma_f32 v190, v32, v36, -v188
	v_fma_f32 v191, v33, v36, v189
	v_add_f32_e32 v36, v190, v123
	v_add_f32_e32 v37, v191, v139
	v_mul_f32_e32 v188, v34, v37
	v_mul_f32_e32 v189, v35, v37
	v_fma_f32 v190, v32, v36, -v188
	v_fma_f32 v191, v33, v36, v189
	v_add_f32_e32 v36, v190, v158
	v_add_f32_e32 v37, v191, v174
	v_mul_f32_e32 v188, v34, v37
	v_mul_f32_e32 v189, v35, v37
	v_fma_f32 v190, v32, v36, -v188
	v_fma_f32 v191, v33, v36, v189
	v_add_f32_e32 v36, v190, v159
	v_add_f32_e32 v37, v191, v175
	v_mul_f32_e32 v188, v34, v37
	v_mul_f32_e32 v189, v35, v37
	v_fma_f32 v190, v32, v36, -v188
	v_fma_f32 v191, v33, v36, v189
	v_add_f32_e32 v36, v190, v160
	v_add_f32_e32 v37, v191, v176
	v_mul_f32_e32 v188, v34, v37
	v_mul_f32_e32 v189, v35, v37
	v_fma_f32 v190, v32, v36, -v188
	v_fma_f32 v191, v33, v36, v189
	v_add_f32_e32 v36, v190, v161
	v_add_f32_e32 v37, v191, v177
	ds_read2_b32 v[178:179], v186 offset0:0 offset1:2
	ds_read2_b32 v[180:181], v186 offset0:4 offset1:6
	ds_read2_b32 v[182:183], v186 offset0:8 offset1:10
	ds_read2_b32 v[184:185], v186 offset0:12 offset1:14
	s_waitcnt lgkmcnt(0)
; __device__ __forceinline__ void s5_pass1(const Params& p, int layer, int task, char* sm) {
;     ...
;   for (int l = 0; l < 128; l++) S5_STEP(sU + l * 16)
	v_add_u32_e32 v186, 0x800, v186
	s_setprio 0
	v_mfma_f32_32x32x2_f32 v[108:123], v178, v16, 0
	v_mfma_f32_32x32x2_f32 v[124:139], v178, v17, 0
	v_mfma_f32_32x32x2_f32 v[146:161], v178, v12, 0
	v_mfma_f32_32x32x2_f32 v[162:177], v178, v13, 0
	v_mfma_f32_32x32x2_f32 v[108:123], v179, v18, v[108:123]
	v_mfma_f32_32x32x2_f32 v[124:139], v179, v19, v[124:139]
	v_mfma_f32_32x32x2_f32 v[146:161], v179, v14, v[146:161]
	v_mfma_f32_32x32x2_f32 v[162:177], v179, v15, v[162:177]
	v_mfma_f32_32x32x2_f32 v[108:123], v180, v20, v[108:123]
	v_mfma_f32_32x32x2_f32 v[124:139], v180, v21, v[124:139]
	v_mfma_f32_32x32x2_f32 v[146:161], v180, v8, v[146:161]
	v_mfma_f32_32x32x2_f32 v[162:177], v180, v9, v[162:177]
	v_mfma_f32_32x32x2_f32 v[108:123], v181, v22, v[108:123]
	v_mfma_f32_32x32x2_f32 v[124:139], v181, v23, v[124:139]
	v_mfma_f32_32x32x2_f32 v[146:161], v181, v10, v[146:161]
	v_mfma_f32_32x32x2_f32 v[162:177], v181, v11, v[162:177]
	v_mfma_f32_32x32x2_f32 v[108:123], v182, v24, v[108:123]
	v_mfma_f32_32x32x2_f32 v[124:139], v182, v25, v[124:139]
	v_mfma_f32_32x32x2_f32 v[146:161], v182, v4, v[146:161]
	v_mfma_f32_32x32x2_f32 v[162:177], v182, v5, v[162:177]
	v_mfma_f32_32x32x2_f32 v[108:123], v183, v26, v[108:123]
	v_mfma_f32_32x32x2_f32 v[124:139], v183, v27, v[124:139]
	v_mfma_f32_32x32x2_f32 v[146:161], v183, v6, v[146:161]
	v_mfma_f32_32x32x2_f32 v[162:177], v183, v7, v[162:177]
	v_mfma_f32_32x32x2_f32 v[108:123], v184, v28, v[108:123]
	v_mfma_f32_32x32x2_f32 v[124:139], v184, v29, v[124:139]
	v_mfma_f32_32x32x2_f32 v[146:161], v184, v0, v[146:161]
	v_mfma_f32_32x32x2_f32 v[162:177], v184, v1, v[162:177]
	v_mfma_f32_32x32x2_f32 v[108:123], v185, v30, v[108:123]
	v_mfma_f32_32x32x2_f32 v[124:139], v185, v31, v[124:139]
	v_mfma_f32_32x32x2_f32 v[146:161], v185, v2, v[146:161]
	v_mfma_f32_32x32x2_f32 v[162:177], v185, v3, v[162:177]
	s_setprio 1
	s_nop 7
	s_nop 7
	s_nop 7
	v_permlane32_swap_b32_e32 v108, v146
	v_permlane32_swap_b32_e32 v124, v162
	v_permlane32_swap_b32_e32 v109, v147
	v_permlane32_swap_b32_e32 v125, v163
	v_permlane32_swap_b32_e32 v110, v148
	v_permlane32_swap_b32_e32 v126, v164
	v_permlane32_swap_b32_e32 v111, v149
	v_permlane32_swap_b32_e32 v127, v165
	v_permlane32_swap_b32_e32 v112, v150
	v_permlane32_swap_b32_e32 v128, v166
	v_permlane32_swap_b32_e32 v113, v151
	v_permlane32_swap_b32_e32 v129, v167
	v_permlane32_swap_b32_e32 v114, v152
	v_permlane32_swap_b32_e32 v130, v168
	v_permlane32_swap_b32_e32 v115, v153
	v_permlane32_swap_b32_e32 v131, v169
	v_permlane32_swap_b32_e32 v116, v154
	v_permlane32_swap_b32_e32 v132, v170
	v_permlane32_swap_b32_e32 v117, v155
	v_permlane32_swap_b32_e32 v133, v171
	v_permlane32_swap_b32_e32 v118, v156
	v_permlane32_swap_b32_e32 v134, v172
	v_permlane32_swap_b32_e32 v119, v157
	v_permlane32_swap_b32_e32 v135, v173
	v_permlane32_swap_b32_e32 v120, v158
	v_permlane32_swap_b32_e32 v136, v174
	v_permlane32_swap_b32_e32 v121, v159
	v_permlane32_swap_b32_e32 v137, v175
	v_permlane32_swap_b32_e32 v122, v160
	v_permlane32_swap_b32_e32 v138, v176
	v_permlane32_swap_b32_e32 v123, v161
	v_permlane32_swap_b32_e32 v139, v177
	v_mul_f32_e32 v188, v34, v37
	v_mul_f32_e32 v189, v35, v37
	v_fma_f32 v190, v32, v36, -v188
	v_fma_f32 v191, v33, v36, v189
	v_add_f32_e32 v36, v190, v108
	v_add_f32_e32 v37, v191, v124
	v_mul_f32_e32 v188, v34, v37
	v_mul_f32_e32 v189, v35, v37
	v_fma_f32 v190, v32, v36, -v188
	v_fma_f32 v191, v33, v36, v189
	v_add_f32_e32 v36, v190, v109
	v_add_f32_e32 v37, v191, v125
	v_mul_f32_e32 v188, v34, v37
	v_mul_f32_e32 v189, v35, v37
	v_fma_f32 v190, v32, v36, -v188
	v_fma_f32 v191, v33, v36, v189
	v_add_f32_e32 v36, v190, v110
	v_add_f32_e32 v37, v191, v126
	v_mul_f32_e32 v188, v34, v37
	v_mul_f32_e32 v189, v35, v37
	v_fma_f32 v190, v32, v36, -v188
	v_fma_f32 v191, v33, v36, v189
	v_add_f32_e32 v36, v190, v111
	v_add_f32_e32 v37, v191, v127
	v_mul_f32_e32 v188, v34, v37
	v_mul_f32_e32 v189, v35, v37
	v_fma_f32 v190, v32, v36, -v188
	v_fma_f32 v191, v33, v36, v189
	v_add_f32_e32 v36, v190, v146
	v_add_f32_e32 v37, v191, v162
	v_mul_f32_e32 v188, v34, v37
	v_mul_f32_e32 v189, v35, v37
	v_fma_f32 v190, v32, v36, -v188
	v_fma_f32 v191, v33, v36, v189
	v_add_f32_e32 v36, v190, v147
	v_add_f32_e32 v37, v191, v163
	v_mul_f32_e32 v188, v34, v37
	v_mul_f32_e32 v189, v35, v37
	v_fma_f32 v190, v32, v36, -v188
	v_fma_f32 v191, v33, v36, v189
	v_add_f32_e32 v36, v190, v148
	v_add_f32_e32 v37, v191, v164
	v_mul_f32_e32 v188, v34, v37
	v_mul_f32_e32 v189, v35, v37
	v_fma_f32 v190, v32, v36, -v188
	v_fma_f32 v191, v33, v36, v189
	v_add_f32_e32 v36, v190, v149
	v_add_f32_e32 v37, v191, v165
	v_mul_f32_e32 v188, v34, v37
	v_mul_f32_e32 v189, v35, v37
	v_fma_f32 v190, v32, v36, -v188
	v_fma_f32 v191, v33, v36, v189
	v_add_f32_e32 v36, v190, v112
	v_add_f32_e32 v37, v191, v128
	v_mul_f32_e32 v188, v34, v37
	v_mul_f32_e32 v189, v35, v37
	v_fma_f32 v190, v32, v36, -v188
	v_fma_f32 v191, v33, v36, v189
	v_add_f32_e32 v36, v190, v113
	v_add_f32_e32 v37, v191, v129
	v_mul_f32_e32 v188, v34, v37
	v_mul_f32_e32 v189, v35, v37
	v_fma_f32 v190, v32, v36, -v188
	v_fma_f32 v191, v33, v36, v189
	v_add_f32_e32 v36, v190, v114
	v_add_f32_e32 v37, v191, v130
	v_mul_f32_e32 v188, v34, v37
	v_mul_f32_e32 v189, v35, v37
	v_fma_f32 v190, v32, v36, -v188
	v_fma_f32 v191, v33, v36, v189
	v_add_f32_e32 v36, v190, v115
	v_add_f32_e32 v37, v191, v131
	v_mul_f32_e32 v188, v34, v37
	v_mul_f32_e32 v189, v35, v37
	v_fma_f32 v190, v32, v36, -v188
	v_fma_f32 v191, v33, v36, v189
	v_add_f32_e32 v36, v190, v150
	v_add_f32_e32 v37, v191, v166
	v_mul_f32_e32 v188, v34, v37
	v_mul_f32_e32 v189, v35, v37
	v_fma_f32 v190, v32, v36, -v188
; __device__ __forceinline__ void s5_pass1(const Params& p, int layer, int task, char* sm) {
;     ...
;   for (int l = 0; l < 128; l++) S5_STEP(sU + l * 16)
	v_fma_f32 v191, v33, v36, v189
	v_add_f32_e32 v36, v190, v151
	v_add_f32_e32 v37, v191, v167
	v_mul_f32_e32 v188, v34, v37
	v_mul_f32_e32 v189, v35, v37
	v_fma_f32 v190, v32, v36, -v188
	v_fma_f32 v191, v33, v36, v189
	v_add_f32_e32 v36, v190, v152
	v_add_f32_e32 v37, v191, v168
	v_mul_f32_e32 v188, v34, v37
	v_mul_f32_e32 v189, v35, v37
	v_fma_f32 v190, v32, v36, -v188
	v_fma_f32 v191, v33, v36, v189
	v_add_f32_e32 v36, v190, v153
	v_add_f32_e32 v37, v191, v169
	v_mul_f32_e32 v188, v34, v37
	v_mul_f32_e32 v189, v35, v37
	v_fma_f32 v190, v32, v36, -v188
	v_fma_f32 v191, v33, v36, v189
	v_add_f32_e32 v36, v190, v116
	v_add_f32_e32 v37, v191, v132
	v_mul_f32_e32 v188, v34, v37
	v_mul_f32_e32 v189, v35, v37
	v_fma_f32 v190, v32, v36, -v188
	v_fma_f32 v191, v33, v36, v189
	v_add_f32_e32 v36, v190, v117
	v_add_f32_e32 v37, v191, v133
	v_mul_f32_e32 v188, v34, v37
	v_mul_f32_e32 v189, v35, v37
	v_fma_f32 v190, v32, v36, -v188
	v_fma_f32 v191, v33, v36, v189
	v_add_f32_e32 v36, v190, v118
	v_add_f32_e32 v37, v191, v134
	v_mul_f32_e32 v188, v34, v37
	v_mul_f32_e32 v189, v35, v37
	v_fma_f32 v190, v32, v36, -v188
	v_fma_f32 v191, v33, v36, v189
	v_add_f32_e32 v36, v190, v119
	v_add_f32_e32 v37, v191, v135
	v_mul_f32_e32 v188, v34, v37
	v_mul_f32_e32 v189, v35, v37
	v_fma_f32 v190, v32, v36, -v188
	v_fma_f32 v191, v33, v36, v189
	v_add_f32_e32 v36, v190, v154
	v_add_f32_e32 v37, v191, v170
	v_mul_f32_e32 v188, v34, v37
	v_mul_f32_e32 v189, v35, v37
	v_fma_f32 v190, v32, v36, -v188
	v_fma_f32 v191, v33, v36, v189
	v_add_f32_e32 v36, v190, v155
	v_add_f32_e32 v37, v191, v171
	v_mul_f32_e32 v188, v34, v37
	v_mul_f32_e32 v189, v35, v37
	v_fma_f32 v190, v32, v36, -v188
	v_fma_f32 v191, v33, v36, v189
	v_add_f32_e32 v36, v190, v156
	v_add_f32_e32 v37, v191, v172
	v_mul_f32_e32 v188, v34, v37
	v_mul_f32_e32 v189, v35, v37
	v_fma_f32 v190, v32, v36, -v188
	v_fma_f32 v191, v33, v36, v189
	v_add_f32_e32 v36, v190, v157
	v_add_f32_e32 v37, v191, v173
	v_mul_f32_e32 v188, v34, v37
	v_mul_f32_e32 v189, v35, v37
	v_fma_f32 v190, v32, v36, -v188
	v_fma_f32 v191, v33, v36, v189
	v_add_f32_e32 v36, v190, v120
	v_add_f32_e32 v37, v191, v136
	v_mul_f32_e32 v188, v34, v37
	v_mul_f32_e32 v189, v35, v37
	v_fma_f32 v190, v32, v36, -v188
	v_fma_f32 v191, v33, v36, v189
	v_add_f32_e32 v36, v190, v121
	v_add_f32_e32 v37, v191, v137
	v_mul_f32_e32 v188, v34, v37
	v_mul_f32_e32 v189, v35, v37
	v_fma_f32 v190, v32, v36, -v188
	v_fma_f32 v191, v33, v36, v189
	v_add_f32_e32 v36, v190, v122
	v_add_f32_e32 v37, v191, v138
	v_mul_f32_e32 v188, v34, v37
	v_mul_f32_e32 v189, v35, v37
	v_fma_f32 v190, v32, v36, -v188
	v_fma_f32 v191, v33, v36, v189
	v_add_f32_e32 v36, v190, v123
	v_add_f32_e32 v37, v191, v139
	v_mul_f32_e32 v188, v34, v37
	v_mul_f32_e32 v189, v35, v37
	v_fma_f32 v190, v32, v36, -v188
	v_fma_f32 v191, v33, v36, v189
	v_add_f32_e32 v36, v190, v158
	v_add_f32_e32 v37, v191, v174
	v_mul_f32_e32 v188, v34, v37
	v_mul_f32_e32 v189, v35, v37
	v_fma_f32 v190, v32, v36, -v188
	v_fma_f32 v191, v33, v36, v189
	v_add_f32_e32 v36, v190, v159
	v_add_f32_e32 v37, v191, v175
	v_mul_f32_e32 v188, v34, v37
	v_mul_f32_e32 v189, v35, v37
	v_fma_f32 v190, v32, v36, -v188
	v_fma_f32 v191, v33, v36, v189
	v_add_f32_e32 v36, v190, v160
	v_add_f32_e32 v37, v191, v176
	v_mul_f32_e32 v188, v34, v37
	v_mul_f32_e32 v189, v35, v37
	v_fma_f32 v190, v32, v36, -v188
	v_fma_f32 v191, v33, v36, v189
	v_add_f32_e32 v36, v190, v161
	v_add_f32_e32 v37, v191, v177
	ds_read2_b32 v[178:179], v186 offset0:0 offset1:2
	ds_read2_b32 v[180:181], v186 offset0:4 offset1:6
	ds_read2_b32 v[182:183], v186 offset0:8 offset1:10
	ds_read2_b32 v[184:185], v186 offset0:12 offset1:14
	s_waitcnt lgkmcnt(0)
	v_add_u32_e32 v186, 0x800, v186
	s_setprio 0
	v_mfma_f32_32x32x2_f32 v[108:123], v178, v16, 0
	v_mfma_f32_32x32x2_f32 v[124:139], v178, v17, 0
	v_mfma_f32_32x32x2_f32 v[146:161], v178, v12, 0
	v_mfma_f32_32x32x2_f32 v[162:177], v178, v13, 0
	v_mfma_f32_32x32x2_f32 v[108:123], v179, v18, v[108:123]
	v_mfma_f32_32x32x2_f32 v[124:139], v179, v19, v[124:139]
	v_mfma_f32_32x32x2_f32 v[146:161], v179, v14, v[146:161]
	v_mfma_f32_32x32x2_f32 v[162:177], v179, v15, v[162:177]
	v_mfma_f32_32x32x2_f32 v[108:123], v180, v20, v[108:123]
	v_mfma_f32_32x32x2_f32 v[124:139], v180, v21, v[124:139]
	v_mfma_f32_32x32x2_f32 v[146:161], v180, v8, v[146:161]
	v_mfma_f32_32x32x2_f32 v[162:177], v180, v9, v[162:177]
	v_mfma_f32_32x32x2_f32 v[108:123], v181, v22, v[108:123]
	v_mfma_f32_32x32x2_f32 v[124:139], v181, v23, v[124:139]
	v_mfma_f32_32x32x2_f32 v[146:161], v181, v10, v[146:161]
	v_mfma_f32_32x32x2_f32 v[162:177], v181, v11, v[162:177]
	v_mfma_f32_32x32x2_f32 v[108:123], v182, v24, v[108:123]
	v_mfma_f32_32x32x2_f32 v[124:139], v182, v25, v[124:139]
	v_mfma_f32_32x32x2_f32 v[146:161], v182, v4, v[146:161]
	v_mfma_f32_32x32x2_f32 v[162:177], v182, v5, v[162:177]
	v_mfma_f32_32x32x2_f32 v[108:123], v183, v26, v[108:123]
	v_mfma_f32_32x32x2_f32 v[124:139], v183, v27, v[124:139]
	v_mfma_f32_32x32x2_f32 v[146:161], v183, v6, v[146:161]
	v_mfma_f32_32x32x2_f32 v[162:177], v183, v7, v[162:177]
	v_mfma_f32_32x32x2_f32 v[108:123], v184, v28, v[108:123]
	v_mfma_f32_32x32x2_f32 v[124:139], v184, v29, v[124:139]
	v_mfma_f32_32x32x2_f32 v[146:161], v184, v0, v[146:161]
	v_mfma_f32_32x32x2_f32 v[162:177], v184, v1, v[162:177]
	v_mfma_f32_32x32x2_f32 v[108:123], v185, v30, v[108:123]
	v_mfma_f32_32x32x2_f32 v[124:139], v185, v31, v[124:139]
	v_mfma_f32_32x32x2_f32 v[146:161], v185, v2, v[146:161]
	v_mfma_f32_32x32x2_f32 v[162:177], v185, v3, v[162:177]
	s_setprio 1
	s_nop 7
	s_nop 7
	s_nop 7
	v_permlane32_swap_b32_e32 v108, v146
; __device__ __forceinline__ void s5_pass1(const Params& p, int layer, int task, char* sm) {
;     ...
;   for (int l = 0; l < 128; l++) S5_STEP(sU + l * 16)
	v_permlane32_swap_b32_e32 v124, v162
	v_permlane32_swap_b32_e32 v109, v147
	v_permlane32_swap_b32_e32 v125, v163
	v_permlane32_swap_b32_e32 v110, v148
	v_permlane32_swap_b32_e32 v126, v164
	v_permlane32_swap_b32_e32 v111, v149
	v_permlane32_swap_b32_e32 v127, v165
	v_permlane32_swap_b32_e32 v112, v150
	v_permlane32_swap_b32_e32 v128, v166
	v_permlane32_swap_b32_e32 v113, v151
	v_permlane32_swap_b32_e32 v129, v167
	v_permlane32_swap_b32_e32 v114, v152
	v_permlane32_swap_b32_e32 v130, v168
	v_permlane32_swap_b32_e32 v115, v153
	v_permlane32_swap_b32_e32 v131, v169
	v_permlane32_swap_b32_e32 v116, v154
	v_permlane32_swap_b32_e32 v132, v170
	v_permlane32_swap_b32_e32 v117, v155
	v_permlane32_swap_b32_e32 v133, v171
	v_permlane32_swap_b32_e32 v118, v156
	v_permlane32_swap_b32_e32 v134, v172
	v_permlane32_swap_b32_e32 v119, v157
	v_permlane32_swap_b32_e32 v135, v173
	v_permlane32_swap_b32_e32 v120, v158
	v_permlane32_swap_b32_e32 v136, v174
	v_permlane32_swap_b32_e32 v121, v159
	v_permlane32_swap_b32_e32 v137, v175
	v_permlane32_swap_b32_e32 v122, v160
	v_permlane32_swap_b32_e32 v138, v176
	v_permlane32_swap_b32_e32 v123, v161
	v_permlane32_swap_b32_e32 v139, v177
	v_mul_f32_e32 v188, v34, v37
	v_mul_f32_e32 v189, v35, v37
	v_fma_f32 v190, v32, v36, -v188
	v_fma_f32 v191, v33, v36, v189
	v_add_f32_e32 v36, v190, v108
	v_add_f32_e32 v37, v191, v124
	v_mul_f32_e32 v188, v34, v37
	v_mul_f32_e32 v189, v35, v37
	v_fma_f32 v190, v32, v36, -v188
	v_fma_f32 v191, v33, v36, v189
	v_add_f32_e32 v36, v190, v109
	v_add_f32_e32 v37, v191, v125
	v_mul_f32_e32 v188, v34, v37
	v_mul_f32_e32 v189, v35, v37
	v_fma_f32 v190, v32, v36, -v188
	v_fma_f32 v191, v33, v36, v189
	v_add_f32_e32 v36, v190, v110
	v_add_f32_e32 v37, v191, v126
	v_mul_f32_e32 v188, v34, v37
	v_mul_f32_e32 v189, v35, v37
	v_fma_f32 v190, v32, v36, -v188
	v_fma_f32 v191, v33, v36, v189
	v_add_f32_e32 v36, v190, v111
	v_add_f32_e32 v37, v191, v127
	v_mul_f32_e32 v188, v34, v37
	v_mul_f32_e32 v189, v35, v37
	v_fma_f32 v190, v32, v36, -v188
	v_fma_f32 v191, v33, v36, v189
	v_add_f32_e32 v36, v190, v146
	v_add_f32_e32 v37, v191, v162
	v_mul_f32_e32 v188, v34, v37
	v_mul_f32_e32 v189, v35, v37
	v_fma_f32 v190, v32, v36, -v188
	v_fma_f32 v191, v33, v36, v189
	v_add_f32_e32 v36, v190, v147
	v_add_f32_e32 v37, v191, v163
	v_mul_f32_e32 v188, v34, v37
	v_mul_f32_e32 v189, v35, v37
	v_fma_f32 v190, v32, v36, -v188
	v_fma_f32 v191, v33, v36, v189
	v_add_f32_e32 v36, v190, v148
	v_add_f32_e32 v37, v191, v164
	v_mul_f32_e32 v188, v34, v37
	v_mul_f32_e32 v189, v35, v37
	v_fma_f32 v190, v32, v36, -v188
	v_fma_f32 v191, v33, v36, v189
	v_add_f32_e32 v36, v190, v149
	v_add_f32_e32 v37, v191, v165
	v_mul_f32_e32 v188, v34, v37
	v_mul_f32_e32 v189, v35, v37
	v_fma_f32 v190, v32, v36, -v188
	v_fma_f32 v191, v33, v36, v189
	v_add_f32_e32 v36, v190, v112
	v_add_f32_e32 v37, v191, v128
	v_mul_f32_e32 v188, v34, v37
	v_mul_f32_e32 v189, v35, v37
	v_fma_f32 v190, v32, v36, -v188
	v_fma_f32 v191, v33, v36, v189
	v_add_f32_e32 v36, v190, v113
	v_add_f32_e32 v37, v191, v129
	v_mul_f32_e32 v188, v34, v37
	v_mul_f32_e32 v189, v35, v37
	v_fma_f32 v190, v32, v36, -v188
	v_fma_f32 v191, v33, v36, v189
	v_add_f32_e32 v36, v190, v114
	v_add_f32_e32 v37, v191, v130
	v_mul_f32_e32 v188, v34, v37
	v_mul_f32_e32 v189, v35, v37
	v_fma_f32 v190, v32, v36, -v188
	v_fma_f32 v191, v33, v36, v189
	v_add_f32_e32 v36, v190, v115
	v_add_f32_e32 v37, v191, v131
	v_mul_f32_e32 v188, v34, v37
	v_mul_f32_e32 v189, v35, v37
	v_fma_f32 v190, v32, v36, -v188
	v_fma_f32 v191, v33, v36, v189
	v_add_f32_e32 v36, v190, v150
	v_add_f32_e32 v37, v191, v166
	v_mul_f32_e32 v188, v34, v37
	v_mul_f32_e32 v189, v35, v37
	v_fma_f32 v190, v32, v36, -v188
	v_fma_f32 v191, v33, v36, v189
	v_add_f32_e32 v36, v190, v151
	v_add_f32_e32 v37, v191, v167
	v_mul_f32_e32 v188, v34, v37
	v_mul_f32_e32 v189, v35, v37
	v_fma_f32 v190, v32, v36, -v188
	v_fma_f32 v191, v33, v36, v189
	v_add_f32_e32 v36, v190, v152
	v_add_f32_e32 v37, v191, v168
	v_mul_f32_e32 v188, v34, v37
	v_mul_f32_e32 v189, v35, v37
	v_fma_f32 v190, v32, v36, -v188
	v_fma_f32 v191, v33, v36, v189
	v_add_f32_e32 v36, v190, v153
	v_add_f32_e32 v37, v191, v169
	v_mul_f32_e32 v188, v34, v37
	v_mul_f32_e32 v189, v35, v37
	v_fma_f32 v190, v32, v36, -v188
	v_fma_f32 v191, v33, v36, v189
	v_add_f32_e32 v36, v190, v116
	v_add_f32_e32 v37, v191, v132
	v_mul_f32_e32 v188, v34, v37
	v_mul_f32_e32 v189, v35, v37
	v_fma_f32 v190, v32, v36, -v188
	v_fma_f32 v191, v33, v36, v189
	v_add_f32_e32 v36, v190, v117
	v_add_f32_e32 v37, v191, v133
	v_mul_f32_e32 v188, v34, v37
	v_mul_f32_e32 v189, v35, v37
	v_fma_f32 v190, v32, v36, -v188
	v_fma_f32 v191, v33, v36, v189
	v_add_f32_e32 v36, v190, v118
	v_add_f32_e32 v37, v191, v134
	v_mul_f32_e32 v188, v34, v37
	v_mul_f32_e32 v189, v35, v37
	v_fma_f32 v190, v32, v36, -v188
	v_fma_f32 v191, v33, v36, v189
	v_add_f32_e32 v36, v190, v119
	v_add_f32_e32 v37, v191, v135
	v_mul_f32_e32 v188, v34, v37
	v_mul_f32_e32 v189, v35, v37
	v_fma_f32 v190, v32, v36, -v188
	v_fma_f32 v191, v33, v36, v189
	v_add_f32_e32 v36, v190, v154
	v_add_f32_e32 v37, v191, v170
	v_mul_f32_e32 v188, v34, v37
	v_mul_f32_e32 v189, v35, v37
	v_fma_f32 v190, v32, v36, -v188
	v_fma_f32 v191, v33, v36, v189
	v_add_f32_e32 v36, v190, v155
	v_add_f32_e32 v37, v191, v171
	v_mul_f32_e32 v188, v34, v37
	v_mul_f32_e32 v189, v35, v37
	v_fma_f32 v190, v32, v36, -v188
	v_fma_f32 v191, v33, v36, v189
	v_add_f32_e32 v36, v190, v156
	v_add_f32_e32 v37, v191, v172
	v_mul_f32_e32 v188, v34, v37
	v_mul_f32_e32 v189, v35, v37
	v_fma_f32 v190, v32, v36, -v188
	v_fma_f32 v191, v33, v36, v189
	v_add_f32_e32 v36, v190, v157
; __device__ __forceinline__ void s5_pass1(const Params& p, int layer, int task, char* sm) {
;     ...
;   for (int l = 0; l < 128; l++) S5_STEP(sU + l * 16)
	v_add_f32_e32 v37, v191, v173
	v_mul_f32_e32 v188, v34, v37
	v_mul_f32_e32 v189, v35, v37
	v_fma_f32 v190, v32, v36, -v188
	v_fma_f32 v191, v33, v36, v189
	v_add_f32_e32 v36, v190, v120
	v_add_f32_e32 v37, v191, v136
	v_mul_f32_e32 v188, v34, v37
	v_mul_f32_e32 v189, v35, v37
	v_fma_f32 v190, v32, v36, -v188
	v_fma_f32 v191, v33, v36, v189
	v_add_f32_e32 v36, v190, v121
	v_add_f32_e32 v37, v191, v137
	v_mul_f32_e32 v188, v34, v37
	v_mul_f32_e32 v189, v35, v37
	v_fma_f32 v190, v32, v36, -v188
	v_fma_f32 v191, v33, v36, v189
	v_add_f32_e32 v36, v190, v122
	v_add_f32_e32 v37, v191, v138
	v_mul_f32_e32 v188, v34, v37
	v_mul_f32_e32 v189, v35, v37
	v_fma_f32 v190, v32, v36, -v188
	v_fma_f32 v191, v33, v36, v189
	v_add_f32_e32 v36, v190, v123
	v_add_f32_e32 v37, v191, v139
	v_mul_f32_e32 v188, v34, v37
	v_mul_f32_e32 v189, v35, v37
	v_fma_f32 v190, v32, v36, -v188
	v_fma_f32 v191, v33, v36, v189
	v_add_f32_e32 v36, v190, v158
	v_add_f32_e32 v37, v191, v174
	v_mul_f32_e32 v188, v34, v37
	v_mul_f32_e32 v189, v35, v37
	v_fma_f32 v190, v32, v36, -v188
	v_fma_f32 v191, v33, v36, v189
	v_add_f32_e32 v36, v190, v159
	v_add_f32_e32 v37, v191, v175
	v_mul_f32_e32 v188, v34, v37
	v_mul_f32_e32 v189, v35, v37
	v_fma_f32 v190, v32, v36, -v188
	v_fma_f32 v191, v33, v36, v189
	v_add_f32_e32 v36, v190, v160
	v_add_f32_e32 v37, v191, v176
	v_mul_f32_e32 v188, v34, v37
	v_mul_f32_e32 v189, v35, v37
	v_fma_f32 v190, v32, v36, -v188
	v_fma_f32 v191, v33, v36, v189
	v_add_f32_e32 v36, v190, v161
	v_add_f32_e32 v37, v191, v177
	ds_read2_b32 v[178:179], v186 offset0:0 offset1:2
	ds_read2_b32 v[180:181], v186 offset0:4 offset1:6
	ds_read2_b32 v[182:183], v186 offset0:8 offset1:10
	ds_read2_b32 v[184:185], v186 offset0:12 offset1:14
	s_waitcnt lgkmcnt(0)
	s_setprio 0
	v_mfma_f32_32x32x2_f32 v[108:123], v178, v16, 0
	v_mfma_f32_32x32x2_f32 v[124:139], v178, v17, 0
	v_mfma_f32_32x32x2_f32 v[146:161], v178, v12, 0
	v_mfma_f32_32x32x2_f32 v[162:177], v178, v13, 0
	v_mfma_f32_32x32x2_f32 v[108:123], v179, v18, v[108:123]
	v_mfma_f32_32x32x2_f32 v[124:139], v179, v19, v[124:139]
	v_mfma_f32_32x32x2_f32 v[146:161], v179, v14, v[146:161]
	v_mfma_f32_32x32x2_f32 v[162:177], v179, v15, v[162:177]
	v_mfma_f32_32x32x2_f32 v[108:123], v180, v20, v[108:123]
	v_mfma_f32_32x32x2_f32 v[124:139], v180, v21, v[124:139]
	v_mfma_f32_32x32x2_f32 v[146:161], v180, v8, v[146:161]
	v_mfma_f32_32x32x2_f32 v[162:177], v180, v9, v[162:177]
	v_mfma_f32_32x32x2_f32 v[108:123], v181, v22, v[108:123]
	v_mfma_f32_32x32x2_f32 v[124:139], v181, v23, v[124:139]
	v_mfma_f32_32x32x2_f32 v[146:161], v181, v10, v[146:161]
	v_mfma_f32_32x32x2_f32 v[162:177], v181, v11, v[162:177]
	v_mfma_f32_32x32x2_f32 v[108:123], v182, v24, v[108:123]
	v_mfma_f32_32x32x2_f32 v[124:139], v182, v25, v[124:139]
	v_mfma_f32_32x32x2_f32 v[146:161], v182, v4, v[146:161]
	v_mfma_f32_32x32x2_f32 v[162:177], v182, v5, v[162:177]
	v_mfma_f32_32x32x2_f32 v[108:123], v183, v26, v[108:123]
	v_mfma_f32_32x32x2_f32 v[124:139], v183, v27, v[124:139]
	v_mfma_f32_32x32x2_f32 v[146:161], v183, v6, v[146:161]
	v_mfma_f32_32x32x2_f32 v[162:177], v183, v7, v[162:177]
	v_mfma_f32_32x32x2_f32 v[108:123], v184, v28, v[108:123]
	v_mfma_f32_32x32x2_f32 v[124:139], v184, v29, v[124:139]
	v_mfma_f32_32x32x2_f32 v[146:161], v184, v0, v[146:161]
	v_mfma_f32_32x32x2_f32 v[162:177], v184, v1, v[162:177]
	v_mfma_f32_32x32x2_f32 v[108:123], v185, v30, v[108:123]
	v_mfma_f32_32x32x2_f32 v[124:139], v185, v31, v[124:139]
	v_mfma_f32_32x32x2_f32 v[146:161], v185, v2, v[146:161]
	v_mfma_f32_32x32x2_f32 v[162:177], v185, v3, v[162:177]
	s_setprio 1
	s_nop 7
	s_nop 7
	s_nop 7
	v_permlane32_swap_b32_e32 v108, v146
	v_permlane32_swap_b32_e32 v124, v162
	v_permlane32_swap_b32_e32 v109, v147
	v_permlane32_swap_b32_e32 v125, v163
	v_permlane32_swap_b32_e32 v110, v148
	v_permlane32_swap_b32_e32 v126, v164
	v_permlane32_swap_b32_e32 v111, v149
	v_permlane32_swap_b32_e32 v127, v165
	v_permlane32_swap_b32_e32 v112, v150
	v_permlane32_swap_b32_e32 v128, v166
	v_permlane32_swap_b32_e32 v113, v151
	v_permlane32_swap_b32_e32 v129, v167
	v_permlane32_swap_b32_e32 v114, v152
	v_permlane32_swap_b32_e32 v130, v168
	v_permlane32_swap_b32_e32 v115, v153
	v_permlane32_swap_b32_e32 v131, v169
	v_permlane32_swap_b32_e32 v116, v154
	v_permlane32_swap_b32_e32 v132, v170
	v_permlane32_swap_b32_e32 v117, v155
	v_permlane32_swap_b32_e32 v133, v171
	v_permlane32_swap_b32_e32 v118, v156
	v_permlane32_swap_b32_e32 v134, v172
	v_permlane32_swap_b32_e32 v119, v157
	v_permlane32_swap_b32_e32 v135, v173
	v_permlane32_swap_b32_e32 v120, v158
	v_permlane32_swap_b32_e32 v136, v174
	v_permlane32_swap_b32_e32 v121, v159
	v_permlane32_swap_b32_e32 v137, v175
	v_permlane32_swap_b32_e32 v122, v160
	v_permlane32_swap_b32_e32 v138, v176
	v_permlane32_swap_b32_e32 v123, v161
	v_permlane32_swap_b32_e32 v139, v177
	v_mul_f32_e32 v188, v34, v37
	v_mul_f32_e32 v189, v35, v37
	v_fma_f32 v190, v32, v36, -v188
	v_fma_f32 v191, v33, v36, v189
	v_add_f32_e32 v36, v190, v108
	v_add_f32_e32 v37, v191, v124
	v_mul_f32_e32 v188, v34, v37
	v_mul_f32_e32 v189, v35, v37
	v_fma_f32 v190, v32, v36, -v188
	v_fma_f32 v191, v33, v36, v189
	v_add_f32_e32 v36, v190, v109
	v_add_f32_e32 v37, v191, v125
	v_mul_f32_e32 v188, v34, v37
	v_mul_f32_e32 v189, v35, v37
	v_fma_f32 v190, v32, v36, -v188
	v_fma_f32 v191, v33, v36, v189
	v_add_f32_e32 v36, v190, v110
	v_add_f32_e32 v37, v191, v126
	v_mul_f32_e32 v188, v34, v37
	v_mul_f32_e32 v189, v35, v37
	v_fma_f32 v190, v32, v36, -v188
	v_fma_f32 v191, v33, v36, v189
	v_add_f32_e32 v36, v190, v111
	v_add_f32_e32 v37, v191, v127
	v_mul_f32_e32 v188, v34, v37
	v_mul_f32_e32 v189, v35, v37
; __device__ __forceinline__ void s5_pass1(const Params& p, int layer, int task, char* sm) {
;     ...
;   for (int l = 0; l < 128; l++) S5_STEP(sU + l * 16)
;   *(float2*)(p.END + (((size_t)(b * 128 + c) * 32 + g) * 64 + lane) * 2) = make_float2(sr, si);
	v_fma_f32 v190, v32, v36, -v188
	v_fma_f32 v191, v33, v36, v189
	v_add_f32_e32 v36, v190, v146
	v_add_f32_e32 v37, v191, v162
	v_mul_f32_e32 v188, v34, v37
	v_mul_f32_e32 v189, v35, v37
	v_fma_f32 v190, v32, v36, -v188
	v_fma_f32 v191, v33, v36, v189
	v_add_f32_e32 v36, v190, v147
	v_add_f32_e32 v37, v191, v163
	v_mul_f32_e32 v188, v34, v37
	v_mul_f32_e32 v189, v35, v37
	v_fma_f32 v190, v32, v36, -v188
	v_fma_f32 v191, v33, v36, v189
	v_add_f32_e32 v36, v190, v148
	v_add_f32_e32 v37, v191, v164
	v_mul_f32_e32 v188, v34, v37
	v_mul_f32_e32 v189, v35, v37
	v_fma_f32 v190, v32, v36, -v188
	v_fma_f32 v191, v33, v36, v189
	v_add_f32_e32 v36, v190, v149
	v_add_f32_e32 v37, v191, v165
	v_mul_f32_e32 v188, v34, v37
	v_mul_f32_e32 v189, v35, v37
	v_fma_f32 v190, v32, v36, -v188
	v_fma_f32 v191, v33, v36, v189
	v_add_f32_e32 v36, v190, v112
	v_add_f32_e32 v37, v191, v128
	v_mul_f32_e32 v188, v34, v37
	v_mul_f32_e32 v189, v35, v37
	v_fma_f32 v190, v32, v36, -v188
	v_fma_f32 v191, v33, v36, v189
	v_add_f32_e32 v36, v190, v113
	v_add_f32_e32 v37, v191, v129
	v_mul_f32_e32 v188, v34, v37
	v_mul_f32_e32 v189, v35, v37
	v_fma_f32 v190, v32, v36, -v188
	v_fma_f32 v191, v33, v36, v189
	v_add_f32_e32 v36, v190, v114
	v_add_f32_e32 v37, v191, v130
	v_mul_f32_e32 v188, v34, v37
	v_mul_f32_e32 v189, v35, v37
	v_fma_f32 v190, v32, v36, -v188
	v_fma_f32 v191, v33, v36, v189
	v_add_f32_e32 v36, v190, v115
	v_add_f32_e32 v37, v191, v131
	v_mul_f32_e32 v188, v34, v37
	v_mul_f32_e32 v189, v35, v37
	v_fma_f32 v190, v32, v36, -v188
	v_fma_f32 v191, v33, v36, v189
	v_add_f32_e32 v36, v190, v150
	v_add_f32_e32 v37, v191, v166
	v_mul_f32_e32 v188, v34, v37
	v_mul_f32_e32 v189, v35, v37
	v_fma_f32 v190, v32, v36, -v188
	v_fma_f32 v191, v33, v36, v189
	v_add_f32_e32 v36, v190, v151
	v_add_f32_e32 v37, v191, v167
	v_mul_f32_e32 v188, v34, v37
	v_mul_f32_e32 v189, v35, v37
	v_fma_f32 v190, v32, v36, -v188
	v_fma_f32 v191, v33, v36, v189
	v_add_f32_e32 v36, v190, v152
	v_add_f32_e32 v37, v191, v168
	v_mul_f32_e32 v188, v34, v37
	v_mul_f32_e32 v189, v35, v37
	v_fma_f32 v190, v32, v36, -v188
	v_fma_f32 v191, v33, v36, v189
	v_add_f32_e32 v36, v190, v153
	v_add_f32_e32 v37, v191, v169
	v_mul_f32_e32 v188, v34, v37
	v_mul_f32_e32 v189, v35, v37
	v_fma_f32 v190, v32, v36, -v188
	v_fma_f32 v191, v33, v36, v189
	v_add_f32_e32 v36, v190, v116
	v_add_f32_e32 v37, v191, v132
	v_mul_f32_e32 v188, v34, v37
	v_mul_f32_e32 v189, v35, v37
	v_fma_f32 v190, v32, v36, -v188
	v_fma_f32 v191, v33, v36, v189
	v_add_f32_e32 v36, v190, v117
	v_add_f32_e32 v37, v191, v133
	v_mul_f32_e32 v188, v34, v37
	v_mul_f32_e32 v189, v35, v37
	v_fma_f32 v190, v32, v36, -v188
	v_fma_f32 v191, v33, v36, v189
	v_add_f32_e32 v36, v190, v118
	v_add_f32_e32 v37, v191, v134
	v_mul_f32_e32 v188, v34, v37
	v_mul_f32_e32 v189, v35, v37
	v_fma_f32 v190, v32, v36, -v188
	v_fma_f32 v191, v33, v36, v189
	v_add_f32_e32 v36, v190, v119
	v_add_f32_e32 v37, v191, v135
	v_mul_f32_e32 v188, v34, v37
	v_mul_f32_e32 v189, v35, v37
	v_fma_f32 v190, v32, v36, -v188
	v_fma_f32 v191, v33, v36, v189
	v_add_f32_e32 v36, v190, v154
	v_add_f32_e32 v37, v191, v170
	v_mul_f32_e32 v188, v34, v37
	v_mul_f32_e32 v189, v35, v37
	v_fma_f32 v190, v32, v36, -v188
	v_fma_f32 v191, v33, v36, v189
	v_add_f32_e32 v36, v190, v155
	v_add_f32_e32 v37, v191, v171
	v_mul_f32_e32 v188, v34, v37
	v_mul_f32_e32 v189, v35, v37
	v_fma_f32 v190, v32, v36, -v188
	v_fma_f32 v191, v33, v36, v189
	v_add_f32_e32 v36, v190, v156
	v_add_f32_e32 v37, v191, v172
	v_mul_f32_e32 v188, v34, v37
	v_mul_f32_e32 v189, v35, v37
	v_fma_f32 v190, v32, v36, -v188
	v_fma_f32 v191, v33, v36, v189
	v_add_f32_e32 v36, v190, v157
	v_add_f32_e32 v37, v191, v173
	v_mul_f32_e32 v188, v34, v37
	v_mul_f32_e32 v189, v35, v37
	v_fma_f32 v190, v32, v36, -v188
	v_fma_f32 v191, v33, v36, v189
	v_add_f32_e32 v36, v190, v120
	v_add_f32_e32 v37, v191, v136
	v_mul_f32_e32 v188, v34, v37
	v_mul_f32_e32 v189, v35, v37
	v_fma_f32 v190, v32, v36, -v188
	v_fma_f32 v191, v33, v36, v189
	v_add_f32_e32 v36, v190, v121
	v_add_f32_e32 v37, v191, v137
	v_mul_f32_e32 v188, v34, v37
	v_mul_f32_e32 v189, v35, v37
	v_fma_f32 v190, v32, v36, -v188
	v_fma_f32 v191, v33, v36, v189
	v_add_f32_e32 v36, v190, v122
	v_add_f32_e32 v37, v191, v138
	v_mul_f32_e32 v188, v34, v37
	v_mul_f32_e32 v189, v35, v37
	v_fma_f32 v190, v32, v36, -v188
	v_fma_f32 v191, v33, v36, v189
	v_add_f32_e32 v36, v190, v123
	v_add_f32_e32 v37, v191, v139
	v_mul_f32_e32 v188, v34, v37
	v_mul_f32_e32 v189, v35, v37
	v_fma_f32 v190, v32, v36, -v188
	v_fma_f32 v191, v33, v36, v189
	v_add_f32_e32 v36, v190, v158
	v_add_f32_e32 v37, v191, v174
	v_mul_f32_e32 v188, v34, v37
	v_mul_f32_e32 v189, v35, v37
	v_fma_f32 v190, v32, v36, -v188
	v_fma_f32 v191, v33, v36, v189
	v_add_f32_e32 v36, v190, v159
	v_add_f32_e32 v37, v191, v175
	v_mul_f32_e32 v188, v34, v37
	v_mul_f32_e32 v189, v35, v37
	v_fma_f32 v190, v32, v36, -v188
	v_fma_f32 v191, v33, v36, v189
	v_add_f32_e32 v36, v190, v160
	v_add_f32_e32 v37, v191, v176
	v_mul_f32_e32 v188, v34, v37
	v_mul_f32_e32 v189, v35, v37
	v_fma_f32 v190, v32, v36, -v188
	v_fma_f32 v191, v33, v36, v189
	v_add_f32_e32 v36, v190, v161
	v_add_f32_e32 v37, v191, v177
	v_mov_b32_e32 v38, v37
	s_setprio 0
	s_lshl_b32 s1, s1, 12
	s_lshl_b32 s0, s0, 5
	s_or_b32 s0, s0, s1
	v_or_b32_e32 v0, s0, v40
	v_lshlrev_b32_e32 v1, 1, v39
	v_readlane_b32 s0, v253, 38
	v_lshl_or_b32 v144, v0, 7, v1
	v_readlane_b32 s1, v253, 39
	v_readlane_b32 s2, v253, 40
	v_readlane_b32 s3, v253, 41
	v_lshl_add_u64 v[0:1], v[144:145], 2, s[0:1]
	v_readlane_b32 s4, v253, 42
	v_readlane_b32 s5, v253, 43
	v_readlane_b32 s6, v253, 44
	v_readlane_b32 s7, v253, 45
	global_store_dwordx2 v[0:1], v[36:37], off

; __device__ __forceinline__ bf f2bf(float f) { return (bf)(pk2(f, 0.f) & 0xFFFFu); }
; __device__ __forceinline__ void s5_pass2(const Params& p, int layer, int task, char* sm) {
;     ...
;       for (int l = 0; l < 32; l++) {
;         S5_STEP(sU + l * 16)
;         sS[l * 136 + lane] = f2bf(sr); sS[l * 136 + 64 + lane] = f2bf(si);
;       }
.LBB0_1796:
	v_add_u32_e32 v103, v79, v40
	v_and_b32_e32 v43, 31, v202
	v_lshrrev_b32_e32 v42, 5, v202
	v_lshlrev_b32_e32 v43, 6, v43
	v_lshl_add_u32 v43, v42, 2, v43
	v_add_u32_e32 v43, v79, v43
	ds_read2_b32 v[170:171], v43 offset0:0 offset1:2
	ds_read2_b32 v[172:173], v43 offset0:4 offset1:6
	ds_read2_b32 v[174:175], v43 offset0:8 offset1:10
	ds_read2_b32 v[176:177], v43 offset0:12 offset1:14
	s_waitcnt lgkmcnt(0)
	s_setprio 0
	v_mfma_f32_32x32x2_f32 v[104:119], v170, v52, 0
	v_mfma_f32_32x32x2_f32 v[120:135], v170, v53, 0
	v_mfma_f32_32x32x2_f32 v[152:167], v170, v20, 0
	v_mfma_f32_32x32x2_f32 v[136:151], v170, v21, 0
	v_mfma_f32_32x32x2_f32 v[104:119], v171, v54, v[104:119]
	v_mfma_f32_32x32x2_f32 v[120:135], v171, v55, v[120:135]
	v_mfma_f32_32x32x2_f32 v[152:167], v171, v22, v[152:167]
	v_mfma_f32_32x32x2_f32 v[136:151], v171, v23, v[136:151]
	v_mfma_f32_32x32x2_f32 v[104:119], v172, v56, v[104:119]
	v_mfma_f32_32x32x2_f32 v[120:135], v172, v57, v[120:135]
	v_mfma_f32_32x32x2_f32 v[152:167], v172, v16, v[152:167]
	v_mfma_f32_32x32x2_f32 v[136:151], v172, v17, v[136:151]
	v_mfma_f32_32x32x2_f32 v[104:119], v173, v58, v[104:119]
	v_mfma_f32_32x32x2_f32 v[120:135], v173, v59, v[120:135]
	v_mfma_f32_32x32x2_f32 v[152:167], v173, v18, v[152:167]
	v_mfma_f32_32x32x2_f32 v[136:151], v173, v19, v[136:151]
	v_mfma_f32_32x32x2_f32 v[104:119], v174, v60, v[104:119]
	v_mfma_f32_32x32x2_f32 v[120:135], v174, v61, v[120:135]
	v_mfma_f32_32x32x2_f32 v[152:167], v174, v12, v[152:167]
	v_mfma_f32_32x32x2_f32 v[136:151], v174, v13, v[136:151]
	v_mfma_f32_32x32x2_f32 v[104:119], v175, v62, v[104:119]
	v_mfma_f32_32x32x2_f32 v[120:135], v175, v63, v[120:135]
	v_mfma_f32_32x32x2_f32 v[152:167], v175, v14, v[152:167]
	v_mfma_f32_32x32x2_f32 v[136:151], v175, v15, v[136:151]
	v_mfma_f32_32x32x2_f32 v[104:119], v176, v64, v[104:119]
	v_mfma_f32_32x32x2_f32 v[120:135], v176, v65, v[120:135]
	v_mfma_f32_32x32x2_f32 v[152:167], v176, v8, v[152:167]
	v_mfma_f32_32x32x2_f32 v[136:151], v176, v9, v[136:151]
	v_mfma_f32_32x32x2_f32 v[104:119], v177, v66, v[104:119]
	v_mfma_f32_32x32x2_f32 v[120:135], v177, v67, v[120:135]
	v_mfma_f32_32x32x2_f32 v[152:167], v177, v10, v[152:167]
	v_mfma_f32_32x32x2_f32 v[136:151], v177, v11, v[136:151]
	s_setprio 1
	s_nop 7
	s_nop 7
	s_nop 7
	v_permlane32_swap_b32_e32 v104, v152
	v_permlane32_swap_b32_e32 v120, v136
	v_permlane32_swap_b32_e32 v105, v153
	v_permlane32_swap_b32_e32 v121, v137
	v_permlane32_swap_b32_e32 v106, v154
	v_permlane32_swap_b32_e32 v122, v138
	v_permlane32_swap_b32_e32 v107, v155
	v_permlane32_swap_b32_e32 v123, v139
	v_permlane32_swap_b32_e32 v108, v156
	v_permlane32_swap_b32_e32 v124, v140
	v_permlane32_swap_b32_e32 v109, v157
	v_permlane32_swap_b32_e32 v125, v141
	v_permlane32_swap_b32_e32 v110, v158
	v_permlane32_swap_b32_e32 v126, v142
	v_permlane32_swap_b32_e32 v111, v159
	v_permlane32_swap_b32_e32 v127, v143
	v_permlane32_swap_b32_e32 v112, v160
	v_permlane32_swap_b32_e32 v128, v144
	v_permlane32_swap_b32_e32 v113, v161
	v_permlane32_swap_b32_e32 v129, v145
	v_permlane32_swap_b32_e32 v114, v162
	v_permlane32_swap_b32_e32 v130, v146
	v_permlane32_swap_b32_e32 v115, v163
	v_permlane32_swap_b32_e32 v131, v147
	v_permlane32_swap_b32_e32 v116, v164
	v_permlane32_swap_b32_e32 v132, v148
	v_permlane32_swap_b32_e32 v117, v165
	v_permlane32_swap_b32_e32 v133, v149
	v_permlane32_swap_b32_e32 v118, v166
	v_permlane32_swap_b32_e32 v134, v150
	v_permlane32_swap_b32_e32 v119, v167
	v_permlane32_swap_b32_e32 v135, v151
	s_waitcnt vmcnt(5)
	v_mul_f32_e32 v76, v74, v71
	v_mul_f32_e32 v77, v75, v71
	v_fma_f32 v40, v68, v70, -v76
	v_fma_f32 v41, v69, v70, v77
	v_add_f32_e32 v70, v40, v104
	v_add_f32_e32 v71, v41, v120
	v_mul_f32_e32 v76, v74, v71
	v_mul_f32_e32 v77, v75, v71
	v_cvt_pk_bf16_f32 v42, v70, v71
	v_fma_f32 v40, v68, v70, -v76
	v_fma_f32 v41, v69, v70, v77
	ds_write_b16 v103, v42
	v_add_f32_e32 v70, v40, v105
	v_add_f32_e32 v71, v41, v121
	ds_write_b16_d16_hi v103, v42 offset:128
	v_mul_f32_e32 v76, v74, v71
	v_mul_f32_e32 v77, v75, v71
	v_cvt_pk_bf16_f32 v42, v70, v71
	v_fma_f32 v40, v68, v70, -v76
	v_fma_f32 v41, v69, v70, v77
	ds_write_b16 v103, v42 offset:272
	v_add_f32_e32 v70, v40, v106
	v_add_f32_e32 v71, v41, v122
	ds_write_b16_d16_hi v103, v42 offset:400
	v_mul_f32_e32 v76, v74, v71
	v_mul_f32_e32 v77, v75, v71
	v_cvt_pk_bf16_f32 v42, v70, v71
	v_fma_f32 v40, v68, v70, -v76
	v_fma_f32 v41, v69, v70, v77
	ds_write_b16 v103, v42 offset:544
	v_add_f32_e32 v70, v40, v107
	v_add_f32_e32 v71, v41, v123
	ds_write_b16_d16_hi v103, v42 offset:672
	v_mul_f32_e32 v76, v74, v71
	v_mul_f32_e32 v77, v75, v71
	v_cvt_pk_bf16_f32 v42, v70, v71
	v_fma_f32 v40, v68, v70, -v76
	v_fma_f32 v41, v69, v70, v77
	ds_write_b16 v103, v42 offset:816
	v_add_f32_e32 v70, v40, v152
	v_add_f32_e32 v71, v41, v136
	ds_write_b16_d16_hi v103, v42 offset:944
	v_mul_f32_e32 v76, v74, v71
	v_mul_f32_e32 v77, v75, v71
	v_cvt_pk_bf16_f32 v42, v70, v71
	v_fma_f32 v40, v68, v70, -v76
	v_fma_f32 v41, v69, v70, v77
	ds_write_b16 v103, v42 offset:1088
	v_add_f32_e32 v70, v40, v153
	v_add_f32_e32 v71, v41, v137
	ds_write_b16_d16_hi v103, v42 offset:1216
	v_mul_f32_e32 v76, v74, v71
	v_mul_f32_e32 v77, v75, v71
	v_cvt_pk_bf16_f32 v42, v70, v71
	v_fma_f32 v40, v68, v70, -v76
	v_fma_f32 v41, v69, v70, v77
	ds_write_b16 v103, v42 offset:1360
	v_add_f32_e32 v70, v40, v154
	v_add_f32_e32 v71, v41, v138
	ds_write_b16_d16_hi v103, v42 offset:1488
	v_mul_f32_e32 v76, v74, v71
	v_mul_f32_e32 v77, v75, v71
	v_cvt_pk_bf16_f32 v42, v70, v71
	v_fma_f32 v40, v68, v70, -v76
	v_fma_f32 v41, v69, v70, v77
	ds_write_b16 v103, v42 offset:1632
	v_add_f32_e32 v70, v40, v155
; __device__ __forceinline__ bf f2bf(float f) { return (bf)(pk2(f, 0.f) & 0xFFFFu); }
; __device__ __forceinline__ void s5_pass2(const Params& p, int layer, int task, char* sm) {
;     ...
;       for (int l = 0; l < 32; l++) {
;         S5_STEP(sU + l * 16)
;         sS[l * 136 + lane] = f2bf(sr); sS[l * 136 + 64 + lane] = f2bf(si);
;       }
	v_add_f32_e32 v71, v41, v139
	ds_write_b16_d16_hi v103, v42 offset:1760
	v_mul_f32_e32 v76, v74, v71
	v_mul_f32_e32 v77, v75, v71
	v_cvt_pk_bf16_f32 v42, v70, v71
	v_fma_f32 v40, v68, v70, -v76
	v_fma_f32 v41, v69, v70, v77
	ds_write_b16 v103, v42 offset:1904
	v_add_f32_e32 v70, v40, v108
	v_add_f32_e32 v71, v41, v124
	ds_write_b16_d16_hi v103, v42 offset:2032
	v_mul_f32_e32 v76, v74, v71
	v_mul_f32_e32 v77, v75, v71
	v_cvt_pk_bf16_f32 v42, v70, v71
	v_fma_f32 v40, v68, v70, -v76
	v_fma_f32 v41, v69, v70, v77
	ds_write_b16 v103, v42 offset:2176
	v_add_f32_e32 v70, v40, v109
	v_add_f32_e32 v71, v41, v125
	ds_write_b16_d16_hi v103, v42 offset:2304
	v_mul_f32_e32 v76, v74, v71
	v_mul_f32_e32 v77, v75, v71
	v_cvt_pk_bf16_f32 v42, v70, v71
	v_fma_f32 v40, v68, v70, -v76
	v_fma_f32 v41, v69, v70, v77
	ds_write_b16 v103, v42 offset:2448
	v_add_f32_e32 v70, v40, v110
	v_add_f32_e32 v71, v41, v126
	ds_write_b16_d16_hi v103, v42 offset:2576
	v_mul_f32_e32 v76, v74, v71
	v_mul_f32_e32 v77, v75, v71
	v_cvt_pk_bf16_f32 v42, v70, v71
	v_fma_f32 v40, v68, v70, -v76
	v_fma_f32 v41, v69, v70, v77
	ds_write_b16 v103, v42 offset:2720
	v_add_f32_e32 v70, v40, v111
	v_add_f32_e32 v71, v41, v127
	ds_write_b16_d16_hi v103, v42 offset:2848
	v_mul_f32_e32 v76, v74, v71
	v_mul_f32_e32 v77, v75, v71
	v_cvt_pk_bf16_f32 v42, v70, v71
	v_fma_f32 v40, v68, v70, -v76
	v_fma_f32 v41, v69, v70, v77
	ds_write_b16 v103, v42 offset:2992
	v_add_f32_e32 v70, v40, v156
	v_add_f32_e32 v71, v41, v140
	ds_write_b16_d16_hi v103, v42 offset:3120
	v_mul_f32_e32 v76, v74, v71
	v_mul_f32_e32 v77, v75, v71
	v_cvt_pk_bf16_f32 v42, v70, v71
	v_fma_f32 v40, v68, v70, -v76
	v_fma_f32 v41, v69, v70, v77
	ds_write_b16 v103, v42 offset:3264
	v_add_f32_e32 v70, v40, v157
	v_add_f32_e32 v71, v41, v141
	ds_write_b16_d16_hi v103, v42 offset:3392
	v_mul_f32_e32 v76, v74, v71
	v_mul_f32_e32 v77, v75, v71
	v_cvt_pk_bf16_f32 v42, v70, v71
	v_fma_f32 v40, v68, v70, -v76
	v_fma_f32 v41, v69, v70, v77
	ds_write_b16 v103, v42 offset:3536
	v_add_f32_e32 v70, v40, v158
	v_add_f32_e32 v71, v41, v142
	ds_write_b16_d16_hi v103, v42 offset:3664
	v_mul_f32_e32 v76, v74, v71
	v_mul_f32_e32 v77, v75, v71
	v_cvt_pk_bf16_f32 v42, v70, v71
	v_fma_f32 v40, v68, v70, -v76
	v_fma_f32 v41, v69, v70, v77
	ds_write_b16 v103, v42 offset:3808
	v_add_f32_e32 v70, v40, v159
	v_add_f32_e32 v71, v41, v143
	ds_write_b16_d16_hi v103, v42 offset:3936
	v_mul_f32_e32 v76, v74, v71
	v_mul_f32_e32 v77, v75, v71
	v_cvt_pk_bf16_f32 v42, v70, v71
	v_fma_f32 v40, v68, v70, -v76
	v_fma_f32 v41, v69, v70, v77
	ds_write_b16 v103, v42 offset:4080
	v_add_f32_e32 v70, v40, v112
	v_add_f32_e32 v71, v41, v128
	ds_write_b16_d16_hi v103, v42 offset:4208
	v_mul_f32_e32 v76, v74, v71
	v_mul_f32_e32 v77, v75, v71
	v_cvt_pk_bf16_f32 v42, v70, v71
	v_fma_f32 v40, v68, v70, -v76
	v_fma_f32 v41, v69, v70, v77
	ds_write_b16 v103, v42 offset:4352
	v_add_f32_e32 v70, v40, v113
	v_add_f32_e32 v71, v41, v129
	ds_write_b16_d16_hi v103, v42 offset:4480
	v_mul_f32_e32 v76, v74, v71
	v_mul_f32_e32 v77, v75, v71
	v_cvt_pk_bf16_f32 v42, v70, v71
	v_fma_f32 v40, v68, v70, -v76
	v_fma_f32 v41, v69, v70, v77
	ds_write_b16 v103, v42 offset:4624
	v_add_f32_e32 v70, v40, v114
	v_add_f32_e32 v71, v41, v130
	ds_write_b16_d16_hi v103, v42 offset:4752
	v_mul_f32_e32 v76, v74, v71
	v_mul_f32_e32 v77, v75, v71
	v_cvt_pk_bf16_f32 v42, v70, v71
	v_fma_f32 v40, v68, v70, -v76
	v_fma_f32 v41, v69, v70, v77
	ds_write_b16 v103, v42 offset:4896
	v_add_f32_e32 v70, v40, v115
	v_add_f32_e32 v71, v41, v131
	ds_write_b16_d16_hi v103, v42 offset:5024
	v_mul_f32_e32 v76, v74, v71
	v_mul_f32_e32 v77, v75, v71
	v_cvt_pk_bf16_f32 v42, v70, v71
	v_fma_f32 v40, v68, v70, -v76
	v_fma_f32 v41, v69, v70, v77
	ds_write_b16 v103, v42 offset:5168
	v_add_f32_e32 v70, v40, v160
	v_add_f32_e32 v71, v41, v144
	ds_write_b16_d16_hi v103, v42 offset:5296
	v_mul_f32_e32 v76, v74, v71
	v_mul_f32_e32 v77, v75, v71
	v_cvt_pk_bf16_f32 v42, v70, v71
	v_fma_f32 v40, v68, v70, -v76
	v_fma_f32 v41, v69, v70, v77
	ds_write_b16 v103, v42 offset:5440
	v_add_f32_e32 v70, v40, v161
	v_add_f32_e32 v71, v41, v145
	ds_write_b16_d16_hi v103, v42 offset:5568
	v_mul_f32_e32 v76, v74, v71
	v_mul_f32_e32 v77, v75, v71
	v_cvt_pk_bf16_f32 v42, v70, v71
	v_fma_f32 v40, v68, v70, -v76
	v_fma_f32 v41, v69, v70, v77
	ds_write_b16 v103, v42 offset:5712
	v_add_f32_e32 v70, v40, v162
	v_add_f32_e32 v71, v41, v146
	ds_write_b16_d16_hi v103, v42 offset:5840
	v_mul_f32_e32 v76, v74, v71
	v_mul_f32_e32 v77, v75, v71
	v_cvt_pk_bf16_f32 v42, v70, v71
	v_fma_f32 v40, v68, v70, -v76
	v_fma_f32 v41, v69, v70, v77
	ds_write_b16 v103, v42 offset:5984
	v_add_f32_e32 v70, v40, v163
	v_add_f32_e32 v71, v41, v147
	ds_write_b16_d16_hi v103, v42 offset:6112
	v_mul_f32_e32 v76, v74, v71
	v_mul_f32_e32 v77, v75, v71
	v_cvt_pk_bf16_f32 v42, v70, v71
	v_fma_f32 v40, v68, v70, -v76
	v_fma_f32 v41, v69, v70, v77
	ds_write_b16 v103, v42 offset:6256
	v_add_f32_e32 v70, v40, v116
	v_add_f32_e32 v71, v41, v132
	ds_write_b16_d16_hi v103, v42 offset:6384
	v_mul_f32_e32 v76, v74, v71
	v_mul_f32_e32 v77, v75, v71
	v_cvt_pk_bf16_f32 v42, v70, v71
	v_fma_f32 v40, v68, v70, -v76
	v_fma_f32 v41, v69, v70, v77
	ds_write_b16 v103, v42 offset:6528
	v_add_f32_e32 v70, v40, v117
	v_add_f32_e32 v71, v41, v133
	ds_write_b16_d16_hi v103, v42 offset:6656
	v_mul_f32_e32 v76, v74, v71
	v_mul_f32_e32 v77, v75, v71
	v_cvt_pk_bf16_f32 v42, v70, v71
	v_fma_f32 v40, v68, v70, -v76
	v_fma_f32 v41, v69, v70, v77
	ds_write_b16 v103, v42 offset:6800
	v_add_f32_e32 v70, v40, v118
	v_add_f32_e32 v71, v41, v134
	ds_write_b16_d16_hi v103, v42 offset:6928
	v_mul_f32_e32 v76, v74, v71
; __device__ __forceinline__ float ozero() { float z = 0.f; asm volatile("" : "+v"(z)); return z; }
; __device__ __forceinline__ bf f2bf(float f) { return (bf)(pk2(f, 0.f) & 0xFFFFu); }
; __device__ __forceinline__ f32x4 mfma16(bf16x8 a, bf16x8 b, f32x4 c) { return __builtin_amdgcn_mfma_f32_16x16x32_bf16(a, b, c, 0, 0, 0); }
; __device__ __forceinline__ void s5_pass2(const Params& p, int layer, int task, char* sm) {
;     ...
;         sS[l * 136 + lane] = f2bf(sr); sS[l * 136 + 64 + lane] = f2bf(si);
;       }
;       __builtin_amdgcn_wave_barrier();
; #pragma unroll
;       for (int mb = 0; mb < 2; mb++) {
;         const float z_ = ozero(); f32x4 acc = {z_, z_, z_, z_};
; #pragma unroll
;         for (int ks = 0; ks < 4; ks++) {
;           bf16x8 af = *(const bf16x8*)(sS + (16 * mb + (lane & 15)) * 136 + ks * 32 + 8 * (lane >> 4));
;           acc = mfma16(af, cf[ks], acc);
;         }
; #pragma unroll
;         for (int r = 0; r < 4; r++) {
;           const int l = 16 * mb + 4 * (lane >> 4) + r;
;           float y = acc[r] + dsk * sU[l * 16 + (lane & 15)];
;           p.YG[(tok0 + sub * 32 + l) * 512 + g * 16 + (lane & 15)] = f2bf(geluf_(y));
	v_mul_f32_e32 v77, v75, v71
	v_cvt_pk_bf16_f32 v42, v70, v71
	v_fma_f32 v40, v68, v70, -v76
	v_fma_f32 v41, v69, v70, v77
	ds_write_b16 v103, v42 offset:7072
	v_add_f32_e32 v70, v40, v119
	v_add_f32_e32 v71, v41, v135
	ds_write_b16_d16_hi v103, v42 offset:7200
	v_mul_f32_e32 v76, v74, v71
	v_mul_f32_e32 v77, v75, v71
	v_cvt_pk_bf16_f32 v42, v70, v71
	v_fma_f32 v40, v68, v70, -v76
	v_fma_f32 v41, v69, v70, v77
	ds_write_b16 v103, v42 offset:7344
	v_add_f32_e32 v70, v40, v164
	v_add_f32_e32 v71, v41, v148
	ds_write_b16_d16_hi v103, v42 offset:7472
	v_mul_f32_e32 v76, v74, v71
	v_mul_f32_e32 v77, v75, v71
	v_cvt_pk_bf16_f32 v42, v70, v71
	v_fma_f32 v40, v68, v70, -v76
	v_fma_f32 v41, v69, v70, v77
	ds_write_b16 v103, v42 offset:7616
	v_add_f32_e32 v70, v40, v165
	v_add_f32_e32 v71, v41, v149
	ds_write_b16_d16_hi v103, v42 offset:7744
	v_mul_f32_e32 v76, v74, v71
	v_mul_f32_e32 v77, v75, v71
	v_cvt_pk_bf16_f32 v42, v70, v71
	v_fma_f32 v40, v68, v70, -v76
	v_fma_f32 v41, v69, v70, v77
	ds_write_b16 v103, v42 offset:7888
	v_add_f32_e32 v70, v40, v166
	v_add_f32_e32 v71, v41, v150
	ds_write_b16_d16_hi v103, v42 offset:8016
	v_mul_f32_e32 v76, v74, v71
	v_mul_f32_e32 v77, v75, v71
	v_cvt_pk_bf16_f32 v42, v70, v71
	v_fma_f32 v40, v68, v70, -v76
	v_fma_f32 v41, v69, v70, v77
	ds_write_b16 v103, v42 offset:8160
	v_add_f32_e32 v70, v40, v167
	v_add_f32_e32 v71, v41, v151
	ds_write_b16_d16_hi v103, v42 offset:8288
	v_cvt_pk_bf16_f32 v42, v70, v71
	ds_write_b16 v103, v42 offset:8432
	ds_write_b16_d16_hi v103, v42 offset:8560
	s_waitcnt lgkmcnt(0)
	v_mov_b32_e32 v145, 0
	s_setprio 0
	v_mov_b32_e32 v40, v145
	ds_read_b128 v[104:107], v100 offset:2048
	ds_read_b32 v76, v83
	v_mov_b32_e32 v41, v40
	v_mov_b32_e32 v42, v40
	v_mov_b32_e32 v43, v40
	s_lshl_b32 s9, s11, 5
	v_mov_b32_e32 v77, s5
	s_cmp_eq_u32 s8, 4
	s_waitcnt vmcnt(4) lgkmcnt(1)
	v_mfma_f32_16x16x32_bf16 v[40:43], v[104:107], v[24:27], v[40:43]
	ds_read_b128 v[104:107], v100 offset:2112
	s_waitcnt vmcnt(3) lgkmcnt(0)
	v_mfma_f32_16x16x32_bf16 v[40:43], v[104:107], v[28:31], v[40:43]
	ds_read_b128 v[104:107], v100 offset:2176
	s_waitcnt vmcnt(2) lgkmcnt(0)
	v_mfma_f32_16x16x32_bf16 v[40:43], v[104:107], v[32:35], v[40:43]
	ds_read_b128 v[104:107], v100 offset:2240
	s_waitcnt vmcnt(1) lgkmcnt(0)
	v_mfma_f32_16x16x32_bf16 v[40:43], v[104:107], v[36:39], v[40:43]
	s_waitcnt vmcnt(0)
	s_nop 6
	v_fma_f32 v40, v102, v76, v40
	v_mul_f32_e32 v76, 0x3d372713, v40
	v_mul_f32_e32 v76, v40, v76
	v_fma_f32 v76, v40, v76, v40
	v_mul_f32_e32 v76, 0x3f4c422a, v76
	v_add_f32_e32 v76, v76, v76
	v_mul_f32_e32 v76, 0x3fb8aa3b, v76
	v_exp_f32_e32 v76, v76
	v_mul_f32_e32 v40, 0.5, v40
	v_add_f32_e32 v76, 1.0, v76
	v_rcp_f32_e32 v76, v76
	s_nop 0
	v_fma_f32 v76, v76, -2.0, 1.0
	v_add_f32_e32 v76, 1.0, v76
	v_mul_f32_e32 v40, v40, v76
	v_or_b32_e32 v76, s9, v82
	v_or_b32_e32 v76, s4, v76
	v_lshlrev_b64 v[104:105], 10, v[76:77]
	v_cvt_pk_bf16_f32 v40, v40, s0
	v_lshl_add_u64 v[104:105], v[72:73], 0, v[104:105]
	global_store_short v[104:105], v40, off
	ds_read_b32 v40, v85
	s_waitcnt lgkmcnt(0)
	v_fma_f32 v40, v102, v40, v41
	v_mul_f32_e32 v41, 0x3d372713, v40
	v_mul_f32_e32 v41, v40, v41
	v_fma_f32 v41, v40, v41, v40
	v_mul_f32_e32 v41, 0x3f4c422a, v41
	v_add_f32_e32 v41, v41, v41
	v_mul_f32_e32 v41, 0x3fb8aa3b, v41
	v_exp_f32_e32 v41, v41
	v_mul_f32_e32 v40, 0.5, v40
	v_add_f32_e32 v41, 1.0, v41
	v_rcp_f32_e32 v41, v41
	s_nop 0
	v_fma_f32 v41, v41, -2.0, 1.0
	v_add_f32_e32 v41, 1.0, v41
	v_mul_f32_e32 v40, v40, v41
	v_cvt_pk_bf16_f32 v103, v40, s0
	v_or_b32_e32 v40, s9, v84
	v_or_b32_e32 v76, s4, v40
	v_lshlrev_b64 v[40:41], 10, v[76:77]
	v_lshl_add_u64 v[40:41], v[72:73], 0, v[40:41]
	global_store_short v[40:41], v103, off
	ds_read_b32 v40, v87
	s_waitcnt lgkmcnt(0)
	v_fma_f32 v40, v102, v40, v42
	v_mul_f32_e32 v41, 0x3d372713, v40
	v_mul_f32_e32 v41, v40, v41
	v_fma_f32 v41, v40, v41, v40
	v_mul_f32_e32 v41, 0x3f4c422a, v41
	v_add_f32_e32 v41, v41, v41
	v_mul_f32_e32 v41, 0x3fb8aa3b, v41
	v_exp_f32_e32 v41, v41
	v_mul_f32_e32 v40, 0.5, v40
	v_add_f32_e32 v41, 1.0, v41
	v_rcp_f32_e32 v41, v41
	s_nop 0
	v_fma_f32 v41, v41, -2.0, 1.0
	v_add_f32_e32 v41, 1.0, v41
	v_mul_f32_e32 v40, v40, v41
	v_cvt_pk_bf16_f32 v42, v40, s0
	v_or_b32_e32 v40, s9, v86
	v_or_b32_e32 v76, s4, v40
	v_lshlrev_b64 v[40:41], 10, v[76:77]
	v_lshl_add_u64 v[40:41], v[72:73], 0, v[40:41]
	global_store_short v[40:41], v42, off
	ds_read_b32 v40, v89
	s_waitcnt lgkmcnt(0)
; __device__ __forceinline__ float ozero() { float z = 0.f; asm volatile("" : "+v"(z)); return z; }
; __device__ __forceinline__ bf f2bf(float f) { return (bf)(pk2(f, 0.f) & 0xFFFFu); }
; __device__ __forceinline__ f32x4 mfma16(bf16x8 a, bf16x8 b, f32x4 c) { return __builtin_amdgcn_mfma_f32_16x16x32_bf16(a, b, c, 0, 0, 0); }
; __device__ __forceinline__ void s5_pass2(const Params& p, int layer, int task, char* sm) {
;     ...
;       for (int mb = 0; mb < 2; mb++) {
;         const float z_ = ozero(); f32x4 acc = {z_, z_, z_, z_};
; #pragma unroll
;         for (int ks = 0; ks < 4; ks++) {
;           bf16x8 af = *(const bf16x8*)(sS + (16 * mb + (lane & 15)) * 136 + ks * 32 + 8 * (lane >> 4));
;           acc = mfma16(af, cf[ks], acc);
;         }
; #pragma unroll
;         for (int r = 0; r < 4; r++) {
;           const int l = 16 * mb + 4 * (lane >> 4) + r;
;           float y = acc[r] + dsk * sU[l * 16 + (lane & 15)];
;           p.YG[(tok0 + sub * 32 + l) * 512 + g * 16 + (lane & 15)] = f2bf(geluf_(y));
;         }
;       }
;     }
	v_fmac_f32_e32 v43, v102, v40
	v_mul_f32_e32 v40, 0x3d372713, v43
	v_mul_f32_e32 v40, v43, v40
	v_fma_f32 v40, v43, v40, v43
	v_mul_f32_e32 v40, 0x3f4c422a, v40
	v_add_f32_e32 v40, v40, v40
	v_mul_f32_e32 v40, 0x3fb8aa3b, v40
	v_exp_f32_e32 v40, v40
	v_mul_f32_e32 v41, 0.5, v43
	v_add_f32_e32 v40, 1.0, v40
	v_rcp_f32_e32 v40, v40
	s_nop 0
	v_fma_f32 v40, v40, -2.0, 1.0
	v_add_f32_e32 v40, 1.0, v40
	v_mul_f32_e32 v40, v41, v40
	v_cvt_pk_bf16_f32 v42, v40, s0
	v_or_b32_e32 v40, s9, v88
	v_or_b32_e32 v76, s4, v40
	v_lshlrev_b64 v[40:41], 10, v[76:77]
	v_lshl_add_u64 v[40:41], v[72:73], 0, v[40:41]
	global_store_short v[40:41], v42, off
	v_mov_b32_e32 v40, v145
	ds_read_b128 v[104:107], v100 offset:6400
	ds_read_b32 v76, v91
	v_mov_b32_e32 v41, v40
	v_mov_b32_e32 v42, v40
	v_mov_b32_e32 v43, v40
	s_waitcnt lgkmcnt(1)
	s_nop 0
	v_mfma_f32_16x16x32_bf16 v[40:43], v[104:107], v[24:27], v[40:43]
	ds_read_b128 v[104:107], v100 offset:6464
	s_waitcnt lgkmcnt(0)
	v_mfma_f32_16x16x32_bf16 v[40:43], v[104:107], v[28:31], v[40:43]
	ds_read_b128 v[104:107], v100 offset:6528
	s_waitcnt lgkmcnt(0)
	v_mfma_f32_16x16x32_bf16 v[40:43], v[104:107], v[32:35], v[40:43]
	ds_read_b128 v[104:107], v100 offset:6592
	s_waitcnt lgkmcnt(0)
	v_mfma_f32_16x16x32_bf16 v[40:43], v[104:107], v[36:39], v[40:43]
	s_nop 7
	v_fma_f32 v40, v102, v76, v40
	v_mul_f32_e32 v76, 0x3d372713, v40
	v_mul_f32_e32 v76, v40, v76
	v_fma_f32 v76, v40, v76, v40
	v_mul_f32_e32 v76, 0x3f4c422a, v76
	v_add_f32_e32 v76, v76, v76
	v_mul_f32_e32 v76, 0x3fb8aa3b, v76
	v_exp_f32_e32 v76, v76
	v_mul_f32_e32 v40, 0.5, v40
	v_add_f32_e32 v76, 1.0, v76
	v_rcp_f32_e32 v76, v76
	s_nop 0
	v_fma_f32 v76, v76, -2.0, 1.0
	v_add_f32_e32 v76, 1.0, v76
	v_mul_f32_e32 v40, v40, v76
	v_or_b32_e32 v76, s9, v90
	v_or_b32_e32 v76, s4, v76
	v_lshlrev_b64 v[104:105], 10, v[76:77]
	v_cvt_pk_bf16_f32 v40, v40, s0
	v_lshl_add_u64 v[104:105], v[72:73], 0, v[104:105]
	global_store_short v[104:105], v40, off
	ds_read_b32 v40, v93
	s_waitcnt lgkmcnt(0)
	v_fma_f32 v40, v102, v40, v41
	v_mul_f32_e32 v41, 0x3d372713, v40
	v_mul_f32_e32 v41, v40, v41
	v_fma_f32 v41, v40, v41, v40
	v_mul_f32_e32 v41, 0x3f4c422a, v41
	v_add_f32_e32 v41, v41, v41
	v_mul_f32_e32 v41, 0x3fb8aa3b, v41
	v_exp_f32_e32 v41, v41
	v_mul_f32_e32 v40, 0.5, v40
	v_add_f32_e32 v41, 1.0, v41
	v_rcp_f32_e32 v41, v41
	s_nop 0
	v_fma_f32 v41, v41, -2.0, 1.0
	v_add_f32_e32 v41, 1.0, v41
	v_mul_f32_e32 v40, v40, v41
	v_cvt_pk_bf16_f32 v103, v40, s0
	v_or_b32_e32 v40, s9, v92
	v_or_b32_e32 v76, s4, v40
	v_lshlrev_b64 v[40:41], 10, v[76:77]
	v_lshl_add_u64 v[40:41], v[72:73], 0, v[40:41]
	global_store_short v[40:41], v103, off
	ds_read_b32 v40, v95
	s_waitcnt lgkmcnt(0)
	v_fma_f32 v40, v102, v40, v42
	v_mul_f32_e32 v41, 0x3d372713, v40
	v_mul_f32_e32 v41, v40, v41
	v_fma_f32 v41, v40, v41, v40
	v_mul_f32_e32 v41, 0x3f4c422a, v41
	v_add_f32_e32 v41, v41, v41
	v_mul_f32_e32 v41, 0x3fb8aa3b, v41
	v_exp_f32_e32 v41, v41
	v_mul_f32_e32 v40, 0.5, v40
	v_add_f32_e32 v41, 1.0, v41
	v_rcp_f32_e32 v41, v41
	s_nop 0
	v_fma_f32 v41, v41, -2.0, 1.0
	v_add_f32_e32 v41, 1.0, v41
	v_mul_f32_e32 v40, v40, v41
	v_cvt_pk_bf16_f32 v42, v40, s0
	v_or_b32_e32 v40, s9, v94
	v_or_b32_e32 v76, s4, v40
	v_lshlrev_b64 v[40:41], 10, v[76:77]
	v_lshl_add_u64 v[40:41], v[72:73], 0, v[40:41]
	global_store_short v[40:41], v42, off
	ds_read_b32 v40, v97
	s_waitcnt lgkmcnt(0)
	v_fmac_f32_e32 v43, v102, v40
	v_mul_f32_e32 v40, 0x3d372713, v43
	v_mul_f32_e32 v40, v43, v40
	v_fma_f32 v40, v43, v40, v43
	v_mul_f32_e32 v40, 0x3f4c422a, v40
	v_add_f32_e32 v40, v40, v40
	v_mul_f32_e32 v40, 0x3fb8aa3b, v40
	v_exp_f32_e32 v40, v40
	v_mul_f32_e32 v41, 0.5, v43
	v_add_f32_e32 v40, 1.0, v40
	v_rcp_f32_e32 v40, v40
	s_nop 0
	v_fma_f32 v40, v40, -2.0, 1.0
	v_add_f32_e32 v40, 1.0, v40
	v_mul_f32_e32 v40, v41, v40
	v_cvt_pk_bf16_f32 v42, v40, s0
	v_or_b32_e32 v40, s9, v96
	v_or_b32_e32 v76, s4, v40
	v_lshlrev_b64 v[40:41], 10, v[76:77]
	v_lshl_add_u64 v[40:41], v[72:73], 0, v[40:41]
	global_store_short v[40:41], v42, off
	s_cbranch_scc1 .LBB0_1789
	s_mov_b32 s11, s8
	s_branch .LBB0_1791

; __device__ __forceinline__ bf f2bf(float f) { return (bf)(pk2(f, 0.f) & 0xFFFFu); }
; __device__ __forceinline__ void s5_pass2(const Params& p, int layer, int task, char* sm) {
;     ...
;       for (int l = 0; l < 32; l++) {
;         S5_STEP(sU + l * 16)
;         sS[l * 136 + lane] = f2bf(sr); sS[l * 136 + 64 + lane] = f2bf(si);
;       }
.LBB0_2060:
	v_add_u32_e32 v103, v79, v40
	v_and_b32_e32 v43, 31, v202
	v_lshrrev_b32_e32 v42, 5, v202
	v_lshlrev_b32_e32 v43, 6, v43
	v_lshl_add_u32 v43, v42, 2, v43
	v_add_u32_e32 v43, v79, v43
	ds_read2_b32 v[170:171], v43 offset0:0 offset1:2
	ds_read2_b32 v[172:173], v43 offset0:4 offset1:6
	ds_read2_b32 v[174:175], v43 offset0:8 offset1:10
	ds_read2_b32 v[176:177], v43 offset0:12 offset1:14
	s_waitcnt lgkmcnt(0)
	s_setprio 0
	v_mfma_f32_32x32x2_f32 v[104:119], v170, v52, 0
	v_mfma_f32_32x32x2_f32 v[120:135], v170, v53, 0
	v_mfma_f32_32x32x2_f32 v[152:167], v170, v20, 0
	v_mfma_f32_32x32x2_f32 v[136:151], v170, v21, 0
	v_mfma_f32_32x32x2_f32 v[104:119], v171, v54, v[104:119]
	v_mfma_f32_32x32x2_f32 v[120:135], v171, v55, v[120:135]
	v_mfma_f32_32x32x2_f32 v[152:167], v171, v22, v[152:167]
	v_mfma_f32_32x32x2_f32 v[136:151], v171, v23, v[136:151]
	v_mfma_f32_32x32x2_f32 v[104:119], v172, v56, v[104:119]
	v_mfma_f32_32x32x2_f32 v[120:135], v172, v57, v[120:135]
	v_mfma_f32_32x32x2_f32 v[152:167], v172, v16, v[152:167]
	v_mfma_f32_32x32x2_f32 v[136:151], v172, v17, v[136:151]
	v_mfma_f32_32x32x2_f32 v[104:119], v173, v58, v[104:119]
	v_mfma_f32_32x32x2_f32 v[120:135], v173, v59, v[120:135]
	v_mfma_f32_32x32x2_f32 v[152:167], v173, v18, v[152:167]
	v_mfma_f32_32x32x2_f32 v[136:151], v173, v19, v[136:151]
	v_mfma_f32_32x32x2_f32 v[104:119], v174, v60, v[104:119]
	v_mfma_f32_32x32x2_f32 v[120:135], v174, v61, v[120:135]
	v_mfma_f32_32x32x2_f32 v[152:167], v174, v12, v[152:167]
	v_mfma_f32_32x32x2_f32 v[136:151], v174, v13, v[136:151]
	v_mfma_f32_32x32x2_f32 v[104:119], v175, v62, v[104:119]
	v_mfma_f32_32x32x2_f32 v[120:135], v175, v63, v[120:135]
	v_mfma_f32_32x32x2_f32 v[152:167], v175, v14, v[152:167]
	v_mfma_f32_32x32x2_f32 v[136:151], v175, v15, v[136:151]
	v_mfma_f32_32x32x2_f32 v[104:119], v176, v64, v[104:119]
	v_mfma_f32_32x32x2_f32 v[120:135], v176, v65, v[120:135]
	v_mfma_f32_32x32x2_f32 v[152:167], v176, v8, v[152:167]
	v_mfma_f32_32x32x2_f32 v[136:151], v176, v9, v[136:151]
	v_mfma_f32_32x32x2_f32 v[104:119], v177, v66, v[104:119]
	v_mfma_f32_32x32x2_f32 v[120:135], v177, v67, v[120:135]
	v_mfma_f32_32x32x2_f32 v[152:167], v177, v10, v[152:167]
	v_mfma_f32_32x32x2_f32 v[136:151], v177, v11, v[136:151]
	s_setprio 1
	s_nop 7
	s_nop 7
	s_nop 7
	v_permlane32_swap_b32_e32 v104, v152
	v_permlane32_swap_b32_e32 v120, v136
	v_permlane32_swap_b32_e32 v105, v153
	v_permlane32_swap_b32_e32 v121, v137
	v_permlane32_swap_b32_e32 v106, v154
	v_permlane32_swap_b32_e32 v122, v138
	v_permlane32_swap_b32_e32 v107, v155
	v_permlane32_swap_b32_e32 v123, v139
	v_permlane32_swap_b32_e32 v108, v156
	v_permlane32_swap_b32_e32 v124, v140
	v_permlane32_swap_b32_e32 v109, v157
	v_permlane32_swap_b32_e32 v125, v141
	v_permlane32_swap_b32_e32 v110, v158
	v_permlane32_swap_b32_e32 v126, v142
	v_permlane32_swap_b32_e32 v111, v159
	v_permlane32_swap_b32_e32 v127, v143
	v_permlane32_swap_b32_e32 v112, v160
	v_permlane32_swap_b32_e32 v128, v144
	v_permlane32_swap_b32_e32 v113, v161
	v_permlane32_swap_b32_e32 v129, v145
	v_permlane32_swap_b32_e32 v114, v162
	v_permlane32_swap_b32_e32 v130, v146
	v_permlane32_swap_b32_e32 v115, v163
	v_permlane32_swap_b32_e32 v131, v147
	v_permlane32_swap_b32_e32 v116, v164
	v_permlane32_swap_b32_e32 v132, v148
	v_permlane32_swap_b32_e32 v117, v165
	v_permlane32_swap_b32_e32 v133, v149
	v_permlane32_swap_b32_e32 v118, v166
	v_permlane32_swap_b32_e32 v134, v150
	v_permlane32_swap_b32_e32 v119, v167
	v_permlane32_swap_b32_e32 v135, v151
	s_waitcnt vmcnt(5)
	v_mul_f32_e32 v76, v74, v71
	v_mul_f32_e32 v77, v75, v71
	v_fma_f32 v40, v68, v70, -v76
	v_fma_f32 v41, v69, v70, v77
	v_add_f32_e32 v70, v40, v104
	v_add_f32_e32 v71, v41, v120
	v_mul_f32_e32 v76, v74, v71
	v_mul_f32_e32 v77, v75, v71
	v_cvt_pk_bf16_f32 v42, v70, v71
	v_fma_f32 v40, v68, v70, -v76
	v_fma_f32 v41, v69, v70, v77
	ds_write_b16 v103, v42
	v_add_f32_e32 v70, v40, v105
	v_add_f32_e32 v71, v41, v121
	ds_write_b16_d16_hi v103, v42 offset:128
	v_mul_f32_e32 v76, v74, v71
	v_mul_f32_e32 v77, v75, v71
	v_cvt_pk_bf16_f32 v42, v70, v71
	v_fma_f32 v40, v68, v70, -v76
	v_fma_f32 v41, v69, v70, v77
	ds_write_b16 v103, v42 offset:272
	v_add_f32_e32 v70, v40, v106
	v_add_f32_e32 v71, v41, v122
	ds_write_b16_d16_hi v103, v42 offset:400
	v_mul_f32_e32 v76, v74, v71
	v_mul_f32_e32 v77, v75, v71
	v_cvt_pk_bf16_f32 v42, v70, v71
	v_fma_f32 v40, v68, v70, -v76
	v_fma_f32 v41, v69, v70, v77
	ds_write_b16 v103, v42 offset:544
	v_add_f32_e32 v70, v40, v107
	v_add_f32_e32 v71, v41, v123
	ds_write_b16_d16_hi v103, v42 offset:672
	v_mul_f32_e32 v76, v74, v71
	v_mul_f32_e32 v77, v75, v71
	v_cvt_pk_bf16_f32 v42, v70, v71
	v_fma_f32 v40, v68, v70, -v76
	v_fma_f32 v41, v69, v70, v77
	ds_write_b16 v103, v42 offset:816
	v_add_f32_e32 v70, v40, v152
	v_add_f32_e32 v71, v41, v136
	ds_write_b16_d16_hi v103, v42 offset:944
	v_mul_f32_e32 v76, v74, v71
	v_mul_f32_e32 v77, v75, v71
	v_cvt_pk_bf16_f32 v42, v70, v71
	v_fma_f32 v40, v68, v70, -v76
	v_fma_f32 v41, v69, v70, v77
	ds_write_b16 v103, v42 offset:1088
	v_add_f32_e32 v70, v40, v153
	v_add_f32_e32 v71, v41, v137
	ds_write_b16_d16_hi v103, v42 offset:1216
	v_mul_f32_e32 v76, v74, v71
	v_mul_f32_e32 v77, v75, v71
	v_cvt_pk_bf16_f32 v42, v70, v71
	v_fma_f32 v40, v68, v70, -v76
	v_fma_f32 v41, v69, v70, v77
	ds_write_b16 v103, v42 offset:1360
	v_add_f32_e32 v70, v40, v154
	v_add_f32_e32 v71, v41, v138
	ds_write_b16_d16_hi v103, v42 offset:1488
	v_mul_f32_e32 v76, v74, v71
	v_mul_f32_e32 v77, v75, v71
	v_cvt_pk_bf16_f32 v42, v70, v71
	v_fma_f32 v40, v68, v70, -v76
	v_fma_f32 v41, v69, v70, v77
	ds_write_b16 v103, v42 offset:1632
	v_add_f32_e32 v70, v40, v155
; __device__ __forceinline__ bf f2bf(float f) { return (bf)(pk2(f, 0.f) & 0xFFFFu); }
; __device__ __forceinline__ void s5_pass2(const Params& p, int layer, int task, char* sm) {
;     ...
;       for (int l = 0; l < 32; l++) {
;         S5_STEP(sU + l * 16)
;         sS[l * 136 + lane] = f2bf(sr); sS[l * 136 + 64 + lane] = f2bf(si);
;       }
	v_add_f32_e32 v71, v41, v139
	ds_write_b16_d16_hi v103, v42 offset:1760
	v_mul_f32_e32 v76, v74, v71
	v_mul_f32_e32 v77, v75, v71
	v_cvt_pk_bf16_f32 v42, v70, v71
	v_fma_f32 v40, v68, v70, -v76
	v_fma_f32 v41, v69, v70, v77
	ds_write_b16 v103, v42 offset:1904
	v_add_f32_e32 v70, v40, v108
	v_add_f32_e32 v71, v41, v124
	ds_write_b16_d16_hi v103, v42 offset:2032
	v_mul_f32_e32 v76, v74, v71
	v_mul_f32_e32 v77, v75, v71
	v_cvt_pk_bf16_f32 v42, v70, v71
	v_fma_f32 v40, v68, v70, -v76
	v_fma_f32 v41, v69, v70, v77
	ds_write_b16 v103, v42 offset:2176
	v_add_f32_e32 v70, v40, v109
	v_add_f32_e32 v71, v41, v125
	ds_write_b16_d16_hi v103, v42 offset:2304
	v_mul_f32_e32 v76, v74, v71
	v_mul_f32_e32 v77, v75, v71
	v_cvt_pk_bf16_f32 v42, v70, v71
	v_fma_f32 v40, v68, v70, -v76
	v_fma_f32 v41, v69, v70, v77
	ds_write_b16 v103, v42 offset:2448
	v_add_f32_e32 v70, v40, v110
	v_add_f32_e32 v71, v41, v126
	ds_write_b16_d16_hi v103, v42 offset:2576
	v_mul_f32_e32 v76, v74, v71
	v_mul_f32_e32 v77, v75, v71
	v_cvt_pk_bf16_f32 v42, v70, v71
	v_fma_f32 v40, v68, v70, -v76
	v_fma_f32 v41, v69, v70, v77
	ds_write_b16 v103, v42 offset:2720
	v_add_f32_e32 v70, v40, v111
	v_add_f32_e32 v71, v41, v127
	ds_write_b16_d16_hi v103, v42 offset:2848
	v_mul_f32_e32 v76, v74, v71
	v_mul_f32_e32 v77, v75, v71
	v_cvt_pk_bf16_f32 v42, v70, v71
	v_fma_f32 v40, v68, v70, -v76
	v_fma_f32 v41, v69, v70, v77
	ds_write_b16 v103, v42 offset:2992
	v_add_f32_e32 v70, v40, v156
	v_add_f32_e32 v71, v41, v140
	ds_write_b16_d16_hi v103, v42 offset:3120
	v_mul_f32_e32 v76, v74, v71
	v_mul_f32_e32 v77, v75, v71
	v_cvt_pk_bf16_f32 v42, v70, v71
	v_fma_f32 v40, v68, v70, -v76
	v_fma_f32 v41, v69, v70, v77
	ds_write_b16 v103, v42 offset:3264
	v_add_f32_e32 v70, v40, v157
	v_add_f32_e32 v71, v41, v141
	ds_write_b16_d16_hi v103, v42 offset:3392
	v_mul_f32_e32 v76, v74, v71
	v_mul_f32_e32 v77, v75, v71
	v_cvt_pk_bf16_f32 v42, v70, v71
	v_fma_f32 v40, v68, v70, -v76
	v_fma_f32 v41, v69, v70, v77
	ds_write_b16 v103, v42 offset:3536
	v_add_f32_e32 v70, v40, v158
	v_add_f32_e32 v71, v41, v142
	ds_write_b16_d16_hi v103, v42 offset:3664
	v_mul_f32_e32 v76, v74, v71
	v_mul_f32_e32 v77, v75, v71
	v_cvt_pk_bf16_f32 v42, v70, v71
	v_fma_f32 v40, v68, v70, -v76
	v_fma_f32 v41, v69, v70, v77
	ds_write_b16 v103, v42 offset:3808
	v_add_f32_e32 v70, v40, v159
	v_add_f32_e32 v71, v41, v143
	ds_write_b16_d16_hi v103, v42 offset:3936
	v_mul_f32_e32 v76, v74, v71
	v_mul_f32_e32 v77, v75, v71
	v_cvt_pk_bf16_f32 v42, v70, v71
	v_fma_f32 v40, v68, v70, -v76
	v_fma_f32 v41, v69, v70, v77
	ds_write_b16 v103, v42 offset:4080
	v_add_f32_e32 v70, v40, v112
	v_add_f32_e32 v71, v41, v128
	ds_write_b16_d16_hi v103, v42 offset:4208
	v_mul_f32_e32 v76, v74, v71
	v_mul_f32_e32 v77, v75, v71
	v_cvt_pk_bf16_f32 v42, v70, v71
	v_fma_f32 v40, v68, v70, -v76
	v_fma_f32 v41, v69, v70, v77
	ds_write_b16 v103, v42 offset:4352
	v_add_f32_e32 v70, v40, v113
	v_add_f32_e32 v71, v41, v129
	ds_write_b16_d16_hi v103, v42 offset:4480
	v_mul_f32_e32 v76, v74, v71
	v_mul_f32_e32 v77, v75, v71
	v_cvt_pk_bf16_f32 v42, v70, v71
	v_fma_f32 v40, v68, v70, -v76
	v_fma_f32 v41, v69, v70, v77
	ds_write_b16 v103, v42 offset:4624
	v_add_f32_e32 v70, v40, v114
	v_add_f32_e32 v71, v41, v130
	ds_write_b16_d16_hi v103, v42 offset:4752
	v_mul_f32_e32 v76, v74, v71
	v_mul_f32_e32 v77, v75, v71
	v_cvt_pk_bf16_f32 v42, v70, v71
	v_fma_f32 v40, v68, v70, -v76
	v_fma_f32 v41, v69, v70, v77
	ds_write_b16 v103, v42 offset:4896
	v_add_f32_e32 v70, v40, v115
	v_add_f32_e32 v71, v41, v131
	ds_write_b16_d16_hi v103, v42 offset:5024
	v_mul_f32_e32 v76, v74, v71
	v_mul_f32_e32 v77, v75, v71
	v_cvt_pk_bf16_f32 v42, v70, v71
	v_fma_f32 v40, v68, v70, -v76
	v_fma_f32 v41, v69, v70, v77
	ds_write_b16 v103, v42 offset:5168
	v_add_f32_e32 v70, v40, v160
	v_add_f32_e32 v71, v41, v144
	ds_write_b16_d16_hi v103, v42 offset:5296
	v_mul_f32_e32 v76, v74, v71
	v_mul_f32_e32 v77, v75, v71
	v_cvt_pk_bf16_f32 v42, v70, v71
	v_fma_f32 v40, v68, v70, -v76
	v_fma_f32 v41, v69, v70, v77
	ds_write_b16 v103, v42 offset:5440
	v_add_f32_e32 v70, v40, v161
	v_add_f32_e32 v71, v41, v145
	ds_write_b16_d16_hi v103, v42 offset:5568
	v_mul_f32_e32 v76, v74, v71
	v_mul_f32_e32 v77, v75, v71
	v_cvt_pk_bf16_f32 v42, v70, v71
	v_fma_f32 v40, v68, v70, -v76
	v_fma_f32 v41, v69, v70, v77
	ds_write_b16 v103, v42 offset:5712
	v_add_f32_e32 v70, v40, v162
	v_add_f32_e32 v71, v41, v146
	ds_write_b16_d16_hi v103, v42 offset:5840
	v_mul_f32_e32 v76, v74, v71
	v_mul_f32_e32 v77, v75, v71
	v_cvt_pk_bf16_f32 v42, v70, v71
	v_fma_f32 v40, v68, v70, -v76
	v_fma_f32 v41, v69, v70, v77
	ds_write_b16 v103, v42 offset:5984
	v_add_f32_e32 v70, v40, v163
	v_add_f32_e32 v71, v41, v147
	ds_write_b16_d16_hi v103, v42 offset:6112
	v_mul_f32_e32 v76, v74, v71
	v_mul_f32_e32 v77, v75, v71
	v_cvt_pk_bf16_f32 v42, v70, v71
	v_fma_f32 v40, v68, v70, -v76
	v_fma_f32 v41, v69, v70, v77
	ds_write_b16 v103, v42 offset:6256
	v_add_f32_e32 v70, v40, v116
	v_add_f32_e32 v71, v41, v132
	ds_write_b16_d16_hi v103, v42 offset:6384
	v_mul_f32_e32 v76, v74, v71
	v_mul_f32_e32 v77, v75, v71
	v_cvt_pk_bf16_f32 v42, v70, v71
	v_fma_f32 v40, v68, v70, -v76
	v_fma_f32 v41, v69, v70, v77
	ds_write_b16 v103, v42 offset:6528
	v_add_f32_e32 v70, v40, v117
	v_add_f32_e32 v71, v41, v133
	ds_write_b16_d16_hi v103, v42 offset:6656
	v_mul_f32_e32 v76, v74, v71
	v_mul_f32_e32 v77, v75, v71
	v_cvt_pk_bf16_f32 v42, v70, v71
	v_fma_f32 v40, v68, v70, -v76
	v_fma_f32 v41, v69, v70, v77
	ds_write_b16 v103, v42 offset:6800
	v_add_f32_e32 v70, v40, v118
	v_add_f32_e32 v71, v41, v134
	ds_write_b16_d16_hi v103, v42 offset:6928
	v_mul_f32_e32 v76, v74, v71
; __device__ __forceinline__ float ozero() { float z = 0.f; asm volatile("" : "+v"(z)); return z; }
; __device__ __forceinline__ bf f2bf(float f) { return (bf)(pk2(f, 0.f) & 0xFFFFu); }
; __device__ __forceinline__ f32x4 mfma16(bf16x8 a, bf16x8 b, f32x4 c) { return __builtin_amdgcn_mfma_f32_16x16x32_bf16(a, b, c, 0, 0, 0); }
; __device__ __forceinline__ void s5_pass2(const Params& p, int layer, int task, char* sm) {
;     ...
;         sS[l * 136 + lane] = f2bf(sr); sS[l * 136 + 64 + lane] = f2bf(si);
;       }
;       __builtin_amdgcn_wave_barrier();
; #pragma unroll
;       for (int mb = 0; mb < 2; mb++) {
;         const float z_ = ozero(); f32x4 acc = {z_, z_, z_, z_};
; #pragma unroll
;         for (int ks = 0; ks < 4; ks++) {
;           bf16x8 af = *(const bf16x8*)(sS + (16 * mb + (lane & 15)) * 136 + ks * 32 + 8 * (lane >> 4));
;           acc = mfma16(af, cf[ks], acc);
;         }
; #pragma unroll
;         for (int r = 0; r < 4; r++) {
;           const int l = 16 * mb + 4 * (lane >> 4) + r;
;           float y = acc[r] + dsk * sU[l * 16 + (lane & 15)];
;           p.YG[(tok0 + sub * 32 + l) * 512 + g * 16 + (lane & 15)] = f2bf(geluf_(y));
	v_mul_f32_e32 v77, v75, v71
	v_cvt_pk_bf16_f32 v42, v70, v71
	v_fma_f32 v40, v68, v70, -v76
	v_fma_f32 v41, v69, v70, v77
	ds_write_b16 v103, v42 offset:7072
	v_add_f32_e32 v70, v40, v119
	v_add_f32_e32 v71, v41, v135
	ds_write_b16_d16_hi v103, v42 offset:7200
	v_mul_f32_e32 v76, v74, v71
	v_mul_f32_e32 v77, v75, v71
	v_cvt_pk_bf16_f32 v42, v70, v71
	v_fma_f32 v40, v68, v70, -v76
	v_fma_f32 v41, v69, v70, v77
	ds_write_b16 v103, v42 offset:7344
	v_add_f32_e32 v70, v40, v164
	v_add_f32_e32 v71, v41, v148
	ds_write_b16_d16_hi v103, v42 offset:7472
	v_mul_f32_e32 v76, v74, v71
	v_mul_f32_e32 v77, v75, v71
	v_cvt_pk_bf16_f32 v42, v70, v71
	v_fma_f32 v40, v68, v70, -v76
	v_fma_f32 v41, v69, v70, v77
	ds_write_b16 v103, v42 offset:7616
	v_add_f32_e32 v70, v40, v165
	v_add_f32_e32 v71, v41, v149
	ds_write_b16_d16_hi v103, v42 offset:7744
	v_mul_f32_e32 v76, v74, v71
	v_mul_f32_e32 v77, v75, v71
	v_cvt_pk_bf16_f32 v42, v70, v71
	v_fma_f32 v40, v68, v70, -v76
	v_fma_f32 v41, v69, v70, v77
	ds_write_b16 v103, v42 offset:7888
	v_add_f32_e32 v70, v40, v166
	v_add_f32_e32 v71, v41, v150
	ds_write_b16_d16_hi v103, v42 offset:8016
	v_mul_f32_e32 v76, v74, v71
	v_mul_f32_e32 v77, v75, v71
	v_cvt_pk_bf16_f32 v42, v70, v71
	v_fma_f32 v40, v68, v70, -v76
	v_fma_f32 v41, v69, v70, v77
	ds_write_b16 v103, v42 offset:8160
	v_add_f32_e32 v70, v40, v167
	v_add_f32_e32 v71, v41, v151
	ds_write_b16_d16_hi v103, v42 offset:8288
	v_cvt_pk_bf16_f32 v42, v70, v71
	ds_write_b16 v103, v42 offset:8432
	ds_write_b16_d16_hi v103, v42 offset:8560
	s_waitcnt lgkmcnt(0)
	v_mov_b32_e32 v145, 0
	s_setprio 0
	v_mov_b32_e32 v40, v145
	ds_read_b128 v[104:107], v100 offset:2048
	ds_read_b32 v76, v83
	v_mov_b32_e32 v41, v40
	v_mov_b32_e32 v42, v40
	v_mov_b32_e32 v43, v40
	s_lshl_b32 s9, s12, 5
	v_mov_b32_e32 v77, s5
	s_cmp_eq_u32 s8, 4
	s_waitcnt vmcnt(4) lgkmcnt(1)
	v_mfma_f32_16x16x32_bf16 v[40:43], v[104:107], v[24:27], v[40:43]
	ds_read_b128 v[104:107], v100 offset:2112
	s_waitcnt vmcnt(3) lgkmcnt(0)
	v_mfma_f32_16x16x32_bf16 v[40:43], v[104:107], v[28:31], v[40:43]
	ds_read_b128 v[104:107], v100 offset:2176
	s_waitcnt vmcnt(2) lgkmcnt(0)
	v_mfma_f32_16x16x32_bf16 v[40:43], v[104:107], v[32:35], v[40:43]
	ds_read_b128 v[104:107], v100 offset:2240
	s_waitcnt vmcnt(1) lgkmcnt(0)
	v_mfma_f32_16x16x32_bf16 v[40:43], v[104:107], v[36:39], v[40:43]
	s_waitcnt vmcnt(0)
	s_nop 6
	v_fma_f32 v40, v102, v76, v40
	v_mul_f32_e32 v76, 0x3d372713, v40
	v_mul_f32_e32 v76, v40, v76
	v_fma_f32 v76, v40, v76, v40
	v_mul_f32_e32 v76, 0x3f4c422a, v76
	v_add_f32_e32 v76, v76, v76
	v_mul_f32_e32 v76, 0x3fb8aa3b, v76
	v_exp_f32_e32 v76, v76
	v_mul_f32_e32 v40, 0.5, v40
	v_add_f32_e32 v76, 1.0, v76
	v_rcp_f32_e32 v76, v76
	s_nop 0
	v_fma_f32 v76, v76, -2.0, 1.0
	v_add_f32_e32 v76, 1.0, v76
	v_mul_f32_e32 v40, v40, v76
	v_or_b32_e32 v76, s9, v82
	v_or_b32_e32 v76, s4, v76
	v_lshlrev_b64 v[104:105], 10, v[76:77]
	v_cvt_pk_bf16_f32 v40, v40, s0
	v_lshl_add_u64 v[104:105], v[72:73], 0, v[104:105]
	global_store_short v[104:105], v40, off
	ds_read_b32 v40, v85
	s_waitcnt lgkmcnt(0)
	v_fma_f32 v40, v102, v40, v41
	v_mul_f32_e32 v41, 0x3d372713, v40
	v_mul_f32_e32 v41, v40, v41
	v_fma_f32 v41, v40, v41, v40
	v_mul_f32_e32 v41, 0x3f4c422a, v41
	v_add_f32_e32 v41, v41, v41
	v_mul_f32_e32 v41, 0x3fb8aa3b, v41
	v_exp_f32_e32 v41, v41
	v_mul_f32_e32 v40, 0.5, v40
	v_add_f32_e32 v41, 1.0, v41
	v_rcp_f32_e32 v41, v41
	s_nop 0
	v_fma_f32 v41, v41, -2.0, 1.0
	v_add_f32_e32 v41, 1.0, v41
	v_mul_f32_e32 v40, v40, v41
	v_cvt_pk_bf16_f32 v103, v40, s0
	v_or_b32_e32 v40, s9, v84
	v_or_b32_e32 v76, s4, v40
	v_lshlrev_b64 v[40:41], 10, v[76:77]
	v_lshl_add_u64 v[40:41], v[72:73], 0, v[40:41]
	global_store_short v[40:41], v103, off
	ds_read_b32 v40, v87
	s_waitcnt lgkmcnt(0)
	v_fma_f32 v40, v102, v40, v42
	v_mul_f32_e32 v41, 0x3d372713, v40
	v_mul_f32_e32 v41, v40, v41
	v_fma_f32 v41, v40, v41, v40
	v_mul_f32_e32 v41, 0x3f4c422a, v41
	v_add_f32_e32 v41, v41, v41
	v_mul_f32_e32 v41, 0x3fb8aa3b, v41
	v_exp_f32_e32 v41, v41
	v_mul_f32_e32 v40, 0.5, v40
	v_add_f32_e32 v41, 1.0, v41
	v_rcp_f32_e32 v41, v41
	s_nop 0
	v_fma_f32 v41, v41, -2.0, 1.0
	v_add_f32_e32 v41, 1.0, v41
	v_mul_f32_e32 v40, v40, v41
	v_cvt_pk_bf16_f32 v42, v40, s0
	v_or_b32_e32 v40, s9, v86
	v_or_b32_e32 v76, s4, v40
	v_lshlrev_b64 v[40:41], 10, v[76:77]
	v_lshl_add_u64 v[40:41], v[72:73], 0, v[40:41]
	global_store_short v[40:41], v42, off
	ds_read_b32 v40, v89
	s_waitcnt lgkmcnt(0)
; __device__ __forceinline__ float ozero() { float z = 0.f; asm volatile("" : "+v"(z)); return z; }
; __device__ __forceinline__ bf f2bf(float f) { return (bf)(pk2(f, 0.f) & 0xFFFFu); }
; __device__ __forceinline__ f32x4 mfma16(bf16x8 a, bf16x8 b, f32x4 c) { return __builtin_amdgcn_mfma_f32_16x16x32_bf16(a, b, c, 0, 0, 0); }
; __device__ __forceinline__ void s5_pass2(const Params& p, int layer, int task, char* sm) {
;     ...
;       for (int mb = 0; mb < 2; mb++) {
;         const float z_ = ozero(); f32x4 acc = {z_, z_, z_, z_};
; #pragma unroll
;         for (int ks = 0; ks < 4; ks++) {
;           bf16x8 af = *(const bf16x8*)(sS + (16 * mb + (lane & 15)) * 136 + ks * 32 + 8 * (lane >> 4));
;           acc = mfma16(af, cf[ks], acc);
;         }
; #pragma unroll
;         for (int r = 0; r < 4; r++) {
;           const int l = 16 * mb + 4 * (lane >> 4) + r;
;           float y = acc[r] + dsk * sU[l * 16 + (lane & 15)];
;           p.YG[(tok0 + sub * 32 + l) * 512 + g * 16 + (lane & 15)] = f2bf(geluf_(y));
;         }
;       }
;     }
	v_fmac_f32_e32 v43, v102, v40
	v_mul_f32_e32 v40, 0x3d372713, v43
	v_mul_f32_e32 v40, v43, v40
	v_fma_f32 v40, v43, v40, v43
	v_mul_f32_e32 v40, 0x3f4c422a, v40
	v_add_f32_e32 v40, v40, v40
	v_mul_f32_e32 v40, 0x3fb8aa3b, v40
	v_exp_f32_e32 v40, v40
	v_mul_f32_e32 v41, 0.5, v43
	v_add_f32_e32 v40, 1.0, v40
	v_rcp_f32_e32 v40, v40
	s_nop 0
	v_fma_f32 v40, v40, -2.0, 1.0
	v_add_f32_e32 v40, 1.0, v40
	v_mul_f32_e32 v40, v41, v40
	v_cvt_pk_bf16_f32 v42, v40, s0
	v_or_b32_e32 v40, s9, v88
	v_or_b32_e32 v76, s4, v40
	v_lshlrev_b64 v[40:41], 10, v[76:77]
	v_lshl_add_u64 v[40:41], v[72:73], 0, v[40:41]
	global_store_short v[40:41], v42, off
	v_mov_b32_e32 v40, v145
	ds_read_b128 v[104:107], v100 offset:6400
	ds_read_b32 v76, v91
	v_mov_b32_e32 v41, v40
	v_mov_b32_e32 v42, v40
	v_mov_b32_e32 v43, v40
	s_waitcnt lgkmcnt(1)
	s_nop 0
	v_mfma_f32_16x16x32_bf16 v[40:43], v[104:107], v[24:27], v[40:43]
	ds_read_b128 v[104:107], v100 offset:6464
	s_waitcnt lgkmcnt(0)
	v_mfma_f32_16x16x32_bf16 v[40:43], v[104:107], v[28:31], v[40:43]
	ds_read_b128 v[104:107], v100 offset:6528
	s_waitcnt lgkmcnt(0)
	v_mfma_f32_16x16x32_bf16 v[40:43], v[104:107], v[32:35], v[40:43]
	ds_read_b128 v[104:107], v100 offset:6592
	s_waitcnt lgkmcnt(0)
	v_mfma_f32_16x16x32_bf16 v[40:43], v[104:107], v[36:39], v[40:43]
	s_nop 7
	v_fma_f32 v40, v102, v76, v40
	v_mul_f32_e32 v76, 0x3d372713, v40
	v_mul_f32_e32 v76, v40, v76
	v_fma_f32 v76, v40, v76, v40
	v_mul_f32_e32 v76, 0x3f4c422a, v76
	v_add_f32_e32 v76, v76, v76
	v_mul_f32_e32 v76, 0x3fb8aa3b, v76
	v_exp_f32_e32 v76, v76
	v_mul_f32_e32 v40, 0.5, v40
	v_add_f32_e32 v76, 1.0, v76
	v_rcp_f32_e32 v76, v76
	s_nop 0
	v_fma_f32 v76, v76, -2.0, 1.0
	v_add_f32_e32 v76, 1.0, v76
	v_mul_f32_e32 v40, v40, v76
	v_or_b32_e32 v76, s9, v90
	v_or_b32_e32 v76, s4, v76
	v_lshlrev_b64 v[104:105], 10, v[76:77]
	v_cvt_pk_bf16_f32 v40, v40, s0
	v_lshl_add_u64 v[104:105], v[72:73], 0, v[104:105]
	global_store_short v[104:105], v40, off
	ds_read_b32 v40, v93
	s_waitcnt lgkmcnt(0)
	v_fma_f32 v40, v102, v40, v41
	v_mul_f32_e32 v41, 0x3d372713, v40
	v_mul_f32_e32 v41, v40, v41
	v_fma_f32 v41, v40, v41, v40
	v_mul_f32_e32 v41, 0x3f4c422a, v41
	v_add_f32_e32 v41, v41, v41
	v_mul_f32_e32 v41, 0x3fb8aa3b, v41
	v_exp_f32_e32 v41, v41
	v_mul_f32_e32 v40, 0.5, v40
	v_add_f32_e32 v41, 1.0, v41
	v_rcp_f32_e32 v41, v41
	s_nop 0
	v_fma_f32 v41, v41, -2.0, 1.0
	v_add_f32_e32 v41, 1.0, v41
	v_mul_f32_e32 v40, v40, v41
	v_cvt_pk_bf16_f32 v103, v40, s0
	v_or_b32_e32 v40, s9, v92
	v_or_b32_e32 v76, s4, v40
	v_lshlrev_b64 v[40:41], 10, v[76:77]
	v_lshl_add_u64 v[40:41], v[72:73], 0, v[40:41]
	global_store_short v[40:41], v103, off
	ds_read_b32 v40, v95
	s_waitcnt lgkmcnt(0)
	v_fma_f32 v40, v102, v40, v42
	v_mul_f32_e32 v41, 0x3d372713, v40
	v_mul_f32_e32 v41, v40, v41
	v_fma_f32 v41, v40, v41, v40
	v_mul_f32_e32 v41, 0x3f4c422a, v41
	v_add_f32_e32 v41, v41, v41
	v_mul_f32_e32 v41, 0x3fb8aa3b, v41
	v_exp_f32_e32 v41, v41
	v_mul_f32_e32 v40, 0.5, v40
	v_add_f32_e32 v41, 1.0, v41
	v_rcp_f32_e32 v41, v41
	s_nop 0
	v_fma_f32 v41, v41, -2.0, 1.0
	v_add_f32_e32 v41, 1.0, v41
	v_mul_f32_e32 v40, v40, v41
	v_cvt_pk_bf16_f32 v42, v40, s0
	v_or_b32_e32 v40, s9, v94
	v_or_b32_e32 v76, s4, v40
	v_lshlrev_b64 v[40:41], 10, v[76:77]
	v_lshl_add_u64 v[40:41], v[72:73], 0, v[40:41]
	global_store_short v[40:41], v42, off
	ds_read_b32 v40, v97
	s_waitcnt lgkmcnt(0)
	v_fmac_f32_e32 v43, v102, v40
	v_mul_f32_e32 v40, 0x3d372713, v43
	v_mul_f32_e32 v40, v43, v40
	v_fma_f32 v40, v43, v40, v43
	v_mul_f32_e32 v40, 0x3f4c422a, v40
	v_add_f32_e32 v40, v40, v40
	v_mul_f32_e32 v40, 0x3fb8aa3b, v40
	v_exp_f32_e32 v40, v40
	v_mul_f32_e32 v41, 0.5, v43
	v_add_f32_e32 v40, 1.0, v40
	v_rcp_f32_e32 v40, v40
	s_nop 0
	v_fma_f32 v40, v40, -2.0, 1.0
	v_add_f32_e32 v40, 1.0, v40
	v_mul_f32_e32 v40, v41, v40
	v_cvt_pk_bf16_f32 v42, v40, s0
	v_or_b32_e32 v40, s9, v96
	v_or_b32_e32 v76, s4, v40
	v_lshlrev_b64 v[40:41], 10, v[76:77]
	v_lshl_add_u64 v[40:41], v[72:73], 0, v[40:41]
	global_store_short v[40:41], v42, off
	s_cbranch_scc1 .LBB0_2053
	s_mov_b32 s12, s8
	s_branch .LBB0_2055
